# adds: chunk-carry scan fused into the LRU pass-C prologue (each workgroup scans AGG for its own head/chunks), separate carry phase and its grid barrier skipped
# speedup vs baseline: 1.0265x; 1.0023x over previous
.LBB0_497:
	s_mul_i32 s0, s96, 5
	s_add_i32 s4, s0, 5
	s_branch .LBB0_577
	s_cmp_le_i32 s70, s4
	s_cselect_b64 s[4:5], -1, 0
	s_and_b64 s[4:5], s[4:5], s[0:1]
	s_mov_b64 s[0:1], -1
	s_and_b64 vcc, exec, s[4:5]
	s_cbranch_vccnz .LBB0_499
	s_mul_i32 s0, s96, 5
	s_add_i32 s4, s0, 5
	s_mov_b64 s[0:1], 0

.LBB0_593:
	s_or_b64 exec, exec, s[42:43]
	v_mul_f32_e32 v8, 0xbfb8aa3b, v8
	v_exp_f32_e32 v10, v8
	s_mov_b32 s1, 0x3f2aaaab
	s_mov_b32 s6, 0x3f317218
	s_mov_b32 s7, 0x7f800000
	v_add_f32_e32 v11, 1.0, v10
	v_frexp_mant_f32_e32 v13, v11
	v_cvt_f64_f32_e32 v[8:9], v11
	v_add_f32_e32 v12, -1.0, v11
	v_frexp_exp_i32_f64_e32 v8, v[8:9]
	v_cmp_gt_f32_e32 vcc, s1, v13
	v_sub_f32_e32 v14, v12, v11
	v_sub_f32_e32 v12, v10, v12
	v_subbrev_co_u32_e32 v8, vcc, 0, v8, vcc
	v_add_f32_e32 v14, 1.0, v14
	v_sub_u32_e32 v9, 0, v8
	v_add_f32_e32 v12, v12, v14
	v_ldexp_f32 v11, v11, v9
	v_ldexp_f32 v9, v12, v9
	v_add_f32_e32 v12, -1.0, v11
	v_add_f32_e32 v15, 1.0, v11
	v_add_f32_e32 v13, 1.0, v12
	v_add_f32_e32 v16, -1.0, v15
	v_sub_f32_e32 v13, v11, v13
	v_sub_f32_e32 v11, v11, v16
	v_add_f32_e32 v13, v9, v13
	v_add_f32_e32 v9, v9, v11
	v_add_f32_e32 v11, v15, v9
	v_rcp_f32_e32 v16, v11
	v_add_f32_e32 v14, v12, v13
	v_sub_f32_e32 v12, v14, v12
	v_sub_f32_e32 v12, v13, v12
	v_sub_f32_e32 v13, v11, v15
	v_sub_f32_e32 v9, v9, v13
	v_mul_f32_e32 v13, v14, v16
	v_mul_f32_e32 v15, v11, v13
	v_fma_f32 v17, v13, v11, -v15
	v_fmac_f32_e32 v17, v13, v9
	v_add_f32_e32 v18, v15, v17
	v_sub_f32_e32 v19, v14, v18
	v_sub_f32_e32 v14, v14, v19
	v_sub_f32_e32 v15, v18, v15
	v_sub_f32_e32 v14, v14, v18
	v_add_f32_e32 v12, v12, v14
	v_sub_f32_e32 v14, v15, v17
	v_add_f32_e32 v12, v14, v12
	v_add_f32_e32 v14, v19, v12
	v_mul_f32_e32 v15, v16, v14
	v_mul_f32_e32 v17, v11, v15
	v_fma_f32 v11, v15, v11, -v17
	v_fmac_f32_e32 v11, v15, v9
	v_sub_f32_e32 v9, v19, v14
	v_add_f32_e32 v9, v12, v9
	v_add_f32_e32 v12, v17, v11
	v_sub_f32_e32 v18, v14, v12
	v_sub_f32_e32 v14, v14, v18
	v_sub_f32_e32 v17, v12, v17
	v_sub_f32_e32 v12, v14, v12
	v_add_f32_e32 v9, v9, v12
	v_sub_f32_e32 v11, v17, v11
	v_cvt_f32_i32_e32 v8, v8
	v_add_f32_e32 v9, v11, v9
	v_add_f32_e32 v11, v13, v15
	v_add_f32_e32 v9, v18, v9
	v_sub_f32_e32 v12, v11, v13
	v_mul_f32_e32 v9, v16, v9
	v_sub_f32_e32 v12, v15, v12
	v_add_f32_e32 v9, v12, v9
	v_mul_f32_e32 v15, 0x3f317218, v8
	v_add_f32_e32 v12, v11, v9
	v_fma_f32 v16, v8, s6, -v15
	v_mul_f32_e32 v13, v12, v12
	v_fmac_f32_e32 v16, 0xb102e308, v8
	v_sub_f32_e32 v8, v12, v11
	v_fmamk_f32 v14, v13, 0x3e9b6dac, v179
	v_sub_f32_e32 v8, v9, v8
	v_add_f32_e32 v9, v15, v16
	v_fmaak_f32 v14, v13, v14, 0x3f2aaada
	v_sub_f32_e32 v11, v9, v15
	v_ldexp_f32 v15, v12, 1
	v_mul_f32_e32 v12, v12, v13
	v_mul_f32_e32 v12, v12, v14
	v_add_f32_e32 v13, v15, v12
	v_sub_f32_e32 v14, v13, v15
	v_ldexp_f32 v8, v8, 1
	v_sub_f32_e32 v12, v12, v14
	v_add_f32_e32 v8, v8, v12
	v_add_f32_e32 v12, v13, v8
	v_sub_f32_e32 v13, v12, v13
	v_sub_f32_e32 v8, v8, v13
	v_add_f32_e32 v13, v9, v12
	v_sub_f32_e32 v14, v13, v9
	v_sub_f32_e32 v15, v13, v14
	v_sub_f32_e32 v11, v16, v11
	v_sub_f32_e32 v9, v9, v15
	v_sub_f32_e32 v12, v12, v14
	v_add_f32_e32 v9, v12, v9
	v_add_f32_e32 v12, v11, v8
	v_sub_f32_e32 v14, v12, v11
	v_sub_f32_e32 v15, v12, v14
	v_sub_f32_e32 v11, v11, v15
	v_sub_f32_e32 v8, v8, v14
	v_add_f32_e32 v9, v12, v9
	v_add_f32_e32 v8, v8, v11
	v_add_f32_e32 v11, v13, v9
	v_sub_f32_e32 v12, v11, v13
	v_sub_f32_e32 v9, v9, v12
	v_add_f32_e32 v8, v8, v9
	v_mul_f32_e32 v7, 0xbfb8aa3b, v7
	v_add_f32_e32 v8, v11, v8
	v_cmp_neq_f32_e32 vcc, s7, v10
	v_exp_f32_e32 v7, v7
	s_mov_b32 s8, 0x33800000
	v_cndmask_b32_e32 v8, v182, v8, vcc
	v_cmp_ngt_f32_e32 vcc, -1.0, v10
	v_cmp_gt_u32_e64 s[42:43], 32, v3
	v_lshl_add_u64 v[72:73], s[44:45], 0, v[144:145]
	v_cndmask_b32_e32 v8, v183, v8, vcc
	v_cmp_neq_f32_e32 vcc, -1.0, v10
	s_mov_b32 s4, 0
	s_waitcnt lgkmcnt(0)
	v_cndmask_b32_e32 v8, v184, v8, vcc
	v_cmp_lt_f32_e64 vcc, |v10|, s8
	s_barrier
	s_nop 0
	v_cndmask_b32_e32 v8, v8, v10, vcc
	v_add_f32_e32 v10, 1.0, v7
	v_mul_f32_e32 v167, 0xc1000000, v8
	v_add_f32_e32 v8, -1.0, v10
	v_sub_f32_e32 v9, v8, v10
	v_add_f32_e32 v9, 1.0, v9
	v_sub_f32_e32 v8, v7, v8
	v_add_f32_e32 v11, v8, v9
	v_frexp_mant_f32_e32 v12, v10
	v_cvt_f64_f32_e32 v[8:9], v10
	v_frexp_exp_i32_f64_e32 v8, v[8:9]
	v_cmp_gt_f32_e32 vcc, s1, v12
	v_readlane_b32 s1, v242, 2
	s_nop 0
	v_subbrev_co_u32_e32 v8, vcc, 0, v8, vcc
	v_sub_u32_e32 v9, 0, v8
	v_ldexp_f32 v10, v10, v9
	v_ldexp_f32 v9, v11, v9
	v_add_f32_e32 v11, -1.0, v10
	v_add_f32_e32 v14, 1.0, v10
	v_add_f32_e32 v12, 1.0, v11
	v_add_f32_e32 v15, -1.0, v14
	v_sub_f32_e32 v12, v10, v12
	v_sub_f32_e32 v10, v10, v15
	v_add_f32_e32 v12, v9, v12
	v_add_f32_e32 v9, v9, v10
	v_add_f32_e32 v10, v14, v9
	v_rcp_f32_e32 v15, v10
	v_add_f32_e32 v13, v11, v12
	v_sub_f32_e32 v11, v13, v11
	v_sub_f32_e32 v11, v12, v11
	v_sub_f32_e32 v12, v10, v14
	v_sub_f32_e32 v9, v9, v12
	v_mul_f32_e32 v12, v13, v15
	v_mul_f32_e32 v14, v10, v12
	v_fma_f32 v16, v12, v10, -v14
	v_fmac_f32_e32 v16, v12, v9
	v_add_f32_e32 v17, v14, v16
	v_sub_f32_e32 v18, v13, v17
	v_sub_f32_e32 v13, v13, v18
	v_sub_f32_e32 v14, v17, v14
	v_sub_f32_e32 v13, v13, v17
	v_add_f32_e32 v11, v11, v13
	v_sub_f32_e32 v13, v14, v16
	v_add_f32_e32 v11, v13, v11
	v_add_f32_e32 v13, v18, v11
	v_mul_f32_e32 v14, v15, v13
	v_mul_f32_e32 v16, v10, v14
	v_fma_f32 v10, v14, v10, -v16
	v_fmac_f32_e32 v10, v14, v9
	v_sub_f32_e32 v9, v18, v13
	v_add_f32_e32 v9, v11, v9
	v_add_f32_e32 v11, v16, v10
	v_sub_f32_e32 v17, v13, v11
	v_sub_f32_e32 v13, v13, v17
	v_sub_f32_e32 v16, v11, v16
	v_sub_f32_e32 v11, v13, v11
	v_add_f32_e32 v9, v9, v11
	v_sub_f32_e32 v10, v16, v10
	v_cvt_f32_i32_e32 v8, v8
	v_add_f32_e32 v9, v10, v9
	v_add_f32_e32 v10, v12, v14
	v_add_f32_e32 v9, v17, v9
	v_sub_f32_e32 v11, v10, v12
	v_mul_f32_e32 v9, v15, v9
	v_sub_f32_e32 v11, v14, v11
	v_add_f32_e32 v9, v11, v9
	v_mul_f32_e32 v14, 0x3f317218, v8
	v_add_f32_e32 v11, v10, v9
	v_fma_f32 v15, v8, s6, -v14
	v_mul_f32_e32 v12, v11, v11
	v_fmac_f32_e32 v15, 0xb102e308, v8
	v_sub_f32_e32 v8, v11, v10
	v_fmamk_f32 v13, v12, 0x3e9b6dac, v179
	v_sub_f32_e32 v8, v9, v8
	v_add_f32_e32 v9, v14, v15
	v_fmaak_f32 v13, v12, v13, 0x3f2aaada
	v_sub_f32_e32 v10, v9, v14
	v_ldexp_f32 v14, v11, 1
	v_mul_f32_e32 v11, v11, v12
	v_mul_f32_e32 v11, v11, v13
	v_add_f32_e32 v12, v14, v11
	v_sub_f32_e32 v13, v12, v14
	v_ldexp_f32 v8, v8, 1
	v_sub_f32_e32 v11, v11, v13
	v_add_f32_e32 v8, v8, v11
	v_add_f32_e32 v11, v12, v8
	v_sub_f32_e32 v12, v11, v12
	v_sub_f32_e32 v8, v8, v12
	v_add_f32_e32 v12, v9, v11
	v_sub_f32_e32 v13, v12, v9
	v_sub_f32_e32 v14, v12, v13
	v_sub_f32_e32 v10, v15, v10
	v_sub_f32_e32 v9, v9, v14
	v_sub_f32_e32 v11, v11, v13
	v_add_f32_e32 v9, v11, v9
	v_add_f32_e32 v11, v10, v8
	v_sub_f32_e32 v13, v11, v10
	v_sub_f32_e32 v14, v11, v13
	v_sub_f32_e32 v10, v10, v14
	v_sub_f32_e32 v8, v8, v13
	v_add_f32_e32 v9, v11, v9
	v_add_f32_e32 v8, v8, v10
	v_add_f32_e32 v10, v12, v9
	v_sub_f32_e32 v11, v10, v12
	v_sub_f32_e32 v9, v9, v11
	v_add_f32_e32 v8, v8, v9
	v_add_f32_e32 v8, v10, v8
	v_cmp_neq_f32_e32 vcc, s7, v7
	v_lshlrev_b32_e32 v9, 2, v0
	v_and_b32_e32 v9, 60, v9
	v_cndmask_b32_e32 v8, v182, v8, vcc
	v_cmp_ngt_f32_e32 vcc, -1.0, v7
	v_lshlrev_b32_e32 v10, 2, v9
	v_readlane_b32 s6, v242, 3
	v_cndmask_b32_e32 v8, v183, v8, vcc
	v_cmp_neq_f32_e32 vcc, -1.0, v7
	v_add_u32_e32 v170, 0, v10
	v_lshlrev_b32_e32 v171, 1, v9
	v_cndmask_b32_e32 v8, v184, v8, vcc
	v_cmp_lt_f32_e64 vcc, |v7|, s8
	v_add_u32_e32 v9, s6, v10
	v_lshl_add_u32 v169, v158, 3, s1
	v_cndmask_b32_e32 v7, v8, v7, vcc
	v_mul_f32_e32 v168, 0xc1000000, v7
	v_ashrrev_i32_e32 v7, 7, v0
	v_lshlrev_b32_e32 v10, 5, v7
	v_or_b32_e32 v5, v10, v5
	s_movk_i32 s1, 0x90
	v_readlane_b32 s7, v242, 4
	v_mul_lo_u32 v5, v5, s1
	v_lshl_add_u32 v14, v158, 2, s6
	v_add_u32_e32 v172, s7, v171
	v_add_u32_e32 v12, s7, v5
	v_lshlrev_b32_e32 v15, 12, v4
	v_and_b32_e32 v0, 0x1fffff80, v0
	v_lshl_add_u64 v[4:5], s[58:59], 0, v[144:145]
	s_mov_b64 s[6:7], 0x11b80000
	v_lshrrev_b32_e32 v8, 5, v3
	v_lshl_add_u32 v173, v0, 3, v169
	v_lshl_add_u64 v[74:75], v[4:5], 0, s[6:7]
	v_or_b32_e32 v0, 3, v2
	s_movk_i32 s6, 0x110
	v_and_b32_e32 v11, -4, v2
	v_mul_lo_u32 v188, v0, s1
	v_mul_lo_u32 v4, v0, s6
	v_lshl_or_b32 v0, v8, 2, v10
	v_lshl_add_u32 v16, v3, 4, 0
	v_mul_lo_u32 v174, v11, s1
	v_mul_lo_u32 v3, v11, s6
	v_mul_lo_u32 v5, v0, s6
	v_mul_lo_u32 v189, v0, s1
	s_lshl_b32 s1, s5, 7
	v_readlane_b32 s6, v243, 22
	s_add_i32 s1, s1, s6
	v_add_u32_e32 v190, s1, v2
	s_ashr_i32 s1, s0, 31
	s_lshl_b64 s[6:7], s[0:1], 12
	s_add_u32 s6, s58, s6
	v_readlane_b32 s1, v243, 59
	v_lshlrev_b32_e32 v144, 2, v1
	s_addc_u32 s7, s59, s7
	s_add_i32 s1, s1, s5
	v_lshlrev_b32_e32 v13, 4, v8
	v_lshl_add_u64 v[0:1], s[6:7], 0, v[144:145]
	s_mov_b64 s[6:7], 0x162eec40
	s_lshl_b32 s1, s1, 7
	v_cmp_lt_i32_e64 s[44:45], 0, v7
	v_cmp_lt_i32_e64 s[46:47], 1, v7
	v_cmp_lt_i32_e64 s[48:49], 2, v7
	v_cmp_gt_i32_e64 s[50:51], 3, v7
	v_cmp_gt_i32_e64 s[52:53], 2, v7
	v_cmp_gt_i32_e64 s[54:55], 1, v7
	v_lshl_add_u64 v[76:77], v[0:1], 0, s[6:7]
	v_add3_u32 v144, v6, s1, -2
	v_add_u32_e32 v191, s1, v2
	v_add_u32_e32 v192, v9, v3
	v_add_u32_e32 v193, v9, v4
	v_add_u32_e32 v194, v12, v13
	v_add_u32_e32 v195, v14, v5
	v_add_u32_e32 v196, v16, v15
	s_mov_b32 s1, 0
	v_mul_f32_e32 v159, 0xbfb8aa3b, v159
	v_mul_f32_e32 v160, 0xbfb8aa3b, v160
	v_mul_f32_e32 v161, 0xbfb8aa3b, v161
	v_mul_f32_e32 v162, 0xbfb8aa3b, v162
	v_mul_f32_e32 v167, 0x3fb8aa3b, v167
	v_mul_f32_e32 v168, 0x3fb8aa3b, v168
	v_and_b32_e32 v23, 63, v175
	s_and_b32 s98, s2, 15
	s_lshl_b32 s98, s98, 9
	v_lshl_add_u32 v20, v23, 3, s98
	s_lshr_b32 s98, s98, 1
	v_lshl_add_u32 v21, v23, 2, s98
	v_lshlrev_b32_e32 v22, 3, v23
	v_add_u32_e32 v22, 0x11c80, v22
	s_and_b64 s[100:101], s[10:11], exec
	s_cselect_b32 s99, 0, 2
	s_lshr_b32 s100, s2, 4
	s_add_i32 s99, s99, s100
	s_and_b32 s99, s99, 15
	v_lshrrev_b32_e32 v23, 6, v175
	s_nop 1
	v_readfirstlane_b32 s98, v23
	s_nop 3
	s_cmp_eq_u32 s98, 1
	s_cbranch_scc1 .Lcf_var_1
	s_cmp_eq_u32 s98, 2
	s_cbranch_scc1 .Lcf_var_2
	s_cmp_eq_u32 s98, 3
	s_cbranch_scc1 .Lcf_var_3
	s_cmp_eq_u32 s98, 4
	s_cbranch_scc1 .Lcf_var_4
	s_cmp_eq_u32 s98, 5
	s_cbranch_scc1 .Lcf_var_5
	s_cmp_eq_u32 s98, 6
	s_cbranch_scc1 .Lcf_var_6
	s_cmp_eq_u32 s98, 7
	s_cbranch_scc1 .Lcf_var_7
.Lcf_var_0:
	s_add_u32 s100, s68, 0x16064c40
	s_addc_u32 s101, s69, 0
	global_load_dwordx2 v[48:49], v20, s[100:101]
	s_add_u32 s100, s68, 0x16066c40
	s_addc_u32 s101, s69, 0
	global_load_dwordx2 v[50:51], v20, s[100:101]
	s_add_u32 s100, s68, 0x16068c40
	s_addc_u32 s101, s69, 0
	global_load_dwordx2 v[52:53], v20, s[100:101]
	s_add_u32 s100, s68, 0x1606ac40
	s_addc_u32 s101, s69, 0
	global_load_dwordx2 v[54:55], v20, s[100:101]
	s_add_u32 s100, s68, 0x1606cc40
	s_addc_u32 s101, s69, 0
	global_load_dwordx2 v[56:57], v20, s[100:101]
	s_add_u32 s100, s68, 0x1606ec40
	s_addc_u32 s101, s69, 0
	global_load_dwordx2 v[58:59], v20, s[100:101]
	s_add_u32 s100, s68, 0x16070c40
	s_addc_u32 s101, s69, 0
	global_load_dwordx2 v[60:61], v20, s[100:101]
	s_add_u32 s100, s68, 0x16072c40
	s_addc_u32 s101, s69, 0
	global_load_dwordx2 v[62:63], v20, s[100:101]
	s_add_u32 s100, s68, 0x16074c40
	s_addc_u32 s101, s69, 0
	global_load_dwordx2 v[64:65], v20, s[100:101]
	s_add_u32 s100, s68, 0x16076c40
	s_addc_u32 s101, s69, 0
	global_load_dwordx2 v[66:67], v20, s[100:101]
	s_add_u32 s100, s68, 0x16078c40
	s_addc_u32 s101, s69, 0
	global_load_dwordx2 v[68:69], v20, s[100:101]
	s_add_u32 s100, s68, 0x1607ac40
	s_addc_u32 s101, s69, 0
	global_load_dwordx2 v[70:71], v20, s[100:101]
	s_add_u32 s100, s68, 0x1607cc40
	s_addc_u32 s101, s69, 0
	global_load_dwordx2 v[78:79], v20, s[100:101]
	s_add_u32 s100, s68, 0x1607ec40
	s_addc_u32 s101, s69, 0
	global_load_dwordx2 v[80:81], v20, s[100:101]
	s_add_u32 s100, s68, 0x16080c40
	s_addc_u32 s101, s69, 0
	global_load_dwordx2 v[82:83], v20, s[100:101]
	s_add_u32 s100, s68, 0x16082c40
	s_addc_u32 s101, s69, 0
	global_load_dwordx2 v[84:85], v20, s[100:101]
	s_add_u32 s100, s68, 0x16084c40
	s_addc_u32 s101, s69, 0
	global_load_dwordx2 v[86:87], v20, s[100:101]
	s_add_u32 s100, s68, 0x16086c40
	s_addc_u32 s101, s69, 0
	global_load_dwordx2 v[88:89], v20, s[100:101]
	s_add_u32 s100, s68, 0x16088c40
	s_addc_u32 s101, s69, 0
	global_load_dwordx2 v[90:91], v20, s[100:101]
	s_add_u32 s100, s68, 0x1608ac40
	s_addc_u32 s101, s69, 0
	global_load_dwordx2 v[92:93], v20, s[100:101]
	s_add_u32 s100, s68, 0x1608cc40
	s_addc_u32 s101, s69, 0
	global_load_dwordx2 v[94:95], v20, s[100:101]
	s_add_u32 s100, s68, 0x1608ec40
	s_addc_u32 s101, s69, 0
	global_load_dwordx2 v[96:97], v20, s[100:101]
	s_add_u32 s100, s68, 0x16090c40
	s_addc_u32 s101, s69, 0
	global_load_dwordx2 v[98:99], v20, s[100:101]
	s_add_u32 s100, s68, 0x16092c40
	s_addc_u32 s101, s69, 0
	global_load_dwordx2 v[100:101], v20, s[100:101]
	s_add_u32 s100, s68, 0x16094c40
	s_addc_u32 s101, s69, 0
	global_load_dwordx2 v[102:103], v20, s[100:101]
	s_add_u32 s100, s68, 0x16096c40
	s_addc_u32 s101, s69, 0
	global_load_dwordx2 v[104:105], v20, s[100:101]
	s_add_u32 s100, s68, 0x16098c40
	s_addc_u32 s101, s69, 0
	global_load_dwordx2 v[106:107], v20, s[100:101]
	s_add_u32 s100, s68, 0x1609ac40
	s_addc_u32 s101, s69, 0
	global_load_dwordx2 v[108:109], v20, s[100:101]
	s_add_u32 s100, s68, 0x1609cc40
	s_addc_u32 s101, s69, 0
	global_load_dwordx2 v[110:111], v20, s[100:101]
	s_add_u32 s100, s68, 0x1609ec40
	s_addc_u32 s101, s69, 0
	global_load_dwordx2 v[112:113], v20, s[100:101]
	s_add_u32 s100, s68, 0x160a0c40
	s_addc_u32 s101, s69, 0
	global_load_dwordx2 v[114:115], v20, s[100:101]
	s_add_u32 s100, s68, 0x160a2c40
	s_addc_u32 s101, s69, 0
	global_load_dwordx2 v[116:117], v20, s[100:101]
	s_add_u32 s100, s68, 0x160a4c40
	s_addc_u32 s101, s69, 0
	global_load_dwordx2 v[118:119], v20, s[100:101]
	v_mov_b32_e32 v24, 1.0
	v_mov_b32_e32 v25, 0
	s_waitcnt vmcnt(32)
	v_fma_f32 v25, v48, v25, v49
	v_mul_f32_e32 v24, v24, v48
	s_waitcnt vmcnt(31)
	v_fma_f32 v25, v50, v25, v51
	v_mul_f32_e32 v24, v24, v50
	s_waitcnt vmcnt(30)
	v_fma_f32 v25, v52, v25, v53
	v_mul_f32_e32 v24, v24, v52
	s_waitcnt vmcnt(29)
	v_fma_f32 v25, v54, v25, v55
	v_mul_f32_e32 v24, v24, v54
	s_waitcnt vmcnt(28)
	v_fma_f32 v25, v56, v25, v57
	v_mul_f32_e32 v24, v24, v56
	s_waitcnt vmcnt(27)
	v_fma_f32 v25, v58, v25, v59
	v_mul_f32_e32 v24, v24, v58
	s_waitcnt vmcnt(26)
	v_fma_f32 v25, v60, v25, v61
	v_mul_f32_e32 v24, v24, v60
	s_waitcnt vmcnt(25)
	v_fma_f32 v25, v62, v25, v63
	v_mul_f32_e32 v24, v24, v62
	s_waitcnt vmcnt(24)
	v_fma_f32 v25, v64, v25, v65
	v_mul_f32_e32 v24, v24, v64
	s_waitcnt vmcnt(23)
	v_fma_f32 v25, v66, v25, v67
	v_mul_f32_e32 v24, v24, v66
	s_waitcnt vmcnt(22)
	v_fma_f32 v25, v68, v25, v69
	v_mul_f32_e32 v24, v24, v68
	s_waitcnt vmcnt(21)
	v_fma_f32 v25, v70, v25, v71
	v_mul_f32_e32 v24, v24, v70
	s_waitcnt vmcnt(20)
	v_fma_f32 v25, v78, v25, v79
	v_mul_f32_e32 v24, v24, v78
	s_waitcnt vmcnt(19)
	v_fma_f32 v25, v80, v25, v81
	v_mul_f32_e32 v24, v24, v80
	s_waitcnt vmcnt(18)
	v_fma_f32 v25, v82, v25, v83
	v_mul_f32_e32 v24, v24, v82
	s_waitcnt vmcnt(17)
	v_fma_f32 v25, v84, v25, v85
	v_mul_f32_e32 v24, v24, v84
	s_waitcnt vmcnt(16)
	v_fma_f32 v25, v86, v25, v87
	v_mul_f32_e32 v24, v24, v86
	s_waitcnt vmcnt(15)
	v_fma_f32 v25, v88, v25, v89
	v_mul_f32_e32 v24, v24, v88
	s_waitcnt vmcnt(14)
	v_fma_f32 v25, v90, v25, v91
	v_mul_f32_e32 v24, v24, v90
	s_waitcnt vmcnt(13)
	v_fma_f32 v25, v92, v25, v93
	v_mul_f32_e32 v24, v24, v92
	s_waitcnt vmcnt(12)
	v_fma_f32 v25, v94, v25, v95
	v_mul_f32_e32 v24, v24, v94
	s_waitcnt vmcnt(11)
	v_fma_f32 v25, v96, v25, v97
	v_mul_f32_e32 v24, v24, v96
	s_waitcnt vmcnt(10)
	v_fma_f32 v25, v98, v25, v99
	v_mul_f32_e32 v24, v24, v98
	s_waitcnt vmcnt(9)
	v_fma_f32 v25, v100, v25, v101
	v_mul_f32_e32 v24, v24, v100
	s_waitcnt vmcnt(8)
	v_fma_f32 v25, v102, v25, v103
	v_mul_f32_e32 v24, v24, v102
	s_waitcnt vmcnt(7)
	v_fma_f32 v25, v104, v25, v105
	v_mul_f32_e32 v24, v24, v104
	s_waitcnt vmcnt(6)
	v_fma_f32 v25, v106, v25, v107
	v_mul_f32_e32 v24, v24, v106
	s_waitcnt vmcnt(5)
	v_fma_f32 v25, v108, v25, v109
	v_mul_f32_e32 v24, v24, v108
	s_waitcnt vmcnt(4)
	v_fma_f32 v25, v110, v25, v111
	v_mul_f32_e32 v24, v24, v110
	s_waitcnt vmcnt(3)
	v_fma_f32 v25, v112, v25, v113
	v_mul_f32_e32 v24, v24, v112
	s_waitcnt vmcnt(2)
	v_fma_f32 v25, v114, v25, v115
	v_mul_f32_e32 v24, v24, v114
	s_waitcnt vmcnt(1)
	v_fma_f32 v25, v116, v25, v117
	v_mul_f32_e32 v24, v24, v116
	s_waitcnt vmcnt(0)
	v_fma_f32 v25, v118, v25, v119
	v_mul_f32_e32 v24, v24, v118
	ds_write_b64 v22, v[24:25] offset:0
	s_waitcnt lgkmcnt(0)
	s_barrier
	v_mov_b32_e32 v26, 0
	s_cmp_eq_u32 s99, 0
	s_cbranch_scc0 .Lcf_skip_0_0
	s_add_u32 s100, s68, 0x1626cc40
	s_addc_u32 s101, s69, 0
	global_store_dword v21, v26, s[100:101]
.Lcf_skip_0_0:
	v_fma_f32 v26, v48, v26, v49
	s_cmp_eq_u32 s99, 1
	s_cbranch_scc0 .Lcf_skip_0_1
	s_add_u32 s100, s68, 0x1626dc40
	s_addc_u32 s101, s69, 0
	global_store_dword v21, v26, s[100:101]
.Lcf_skip_0_1:
	v_fma_f32 v26, v50, v26, v51
	s_cmp_eq_u32 s99, 2
	s_cbranch_scc0 .Lcf_skip_0_2
	s_add_u32 s100, s68, 0x1626ec40
	s_addc_u32 s101, s69, 0
	global_store_dword v21, v26, s[100:101]
.Lcf_skip_0_2:
	v_fma_f32 v26, v52, v26, v53
	s_cmp_eq_u32 s99, 3
	s_cbranch_scc0 .Lcf_skip_0_3
	s_add_u32 s100, s68, 0x1626fc40
	s_addc_u32 s101, s69, 0
	global_store_dword v21, v26, s[100:101]
.Lcf_skip_0_3:
	v_fma_f32 v26, v54, v26, v55
	s_cmp_eq_u32 s99, 4
	s_cbranch_scc0 .Lcf_skip_0_4
	s_add_u32 s100, s68, 0x16270c40
	s_addc_u32 s101, s69, 0
	global_store_dword v21, v26, s[100:101]
.Lcf_skip_0_4:
	v_fma_f32 v26, v56, v26, v57
	s_cmp_eq_u32 s99, 5
	s_cbranch_scc0 .Lcf_skip_0_5
	s_add_u32 s100, s68, 0x16271c40
	s_addc_u32 s101, s69, 0
	global_store_dword v21, v26, s[100:101]
.Lcf_skip_0_5:
	v_fma_f32 v26, v58, v26, v59
	s_cmp_eq_u32 s99, 6
	s_cbranch_scc0 .Lcf_skip_0_6
	s_add_u32 s100, s68, 0x16272c40
	s_addc_u32 s101, s69, 0
	global_store_dword v21, v26, s[100:101]
.Lcf_skip_0_6:
	v_fma_f32 v26, v60, v26, v61
	s_cmp_eq_u32 s99, 7
	s_cbranch_scc0 .Lcf_skip_0_7
	s_add_u32 s100, s68, 0x16273c40
	s_addc_u32 s101, s69, 0
	global_store_dword v21, v26, s[100:101]
.Lcf_skip_0_7:
	v_fma_f32 v26, v62, v26, v63
	s_cmp_eq_u32 s99, 8
	s_cbranch_scc0 .Lcf_skip_0_8
	s_add_u32 s100, s68, 0x16274c40
	s_addc_u32 s101, s69, 0
	global_store_dword v21, v26, s[100:101]
.Lcf_skip_0_8:
	v_fma_f32 v26, v64, v26, v65
	s_cmp_eq_u32 s99, 9
	s_cbranch_scc0 .Lcf_skip_0_9
	s_add_u32 s100, s68, 0x16275c40
	s_addc_u32 s101, s69, 0
	global_store_dword v21, v26, s[100:101]
.Lcf_skip_0_9:
	v_fma_f32 v26, v66, v26, v67
	s_cmp_eq_u32 s99, 10
	s_cbranch_scc0 .Lcf_skip_0_10
	s_add_u32 s100, s68, 0x16276c40
	s_addc_u32 s101, s69, 0
	global_store_dword v21, v26, s[100:101]
.Lcf_skip_0_10:
	v_fma_f32 v26, v68, v26, v69
	s_cmp_eq_u32 s99, 11
	s_cbranch_scc0 .Lcf_skip_0_11
	s_add_u32 s100, s68, 0x16277c40
	s_addc_u32 s101, s69, 0
	global_store_dword v21, v26, s[100:101]
.Lcf_skip_0_11:
	v_fma_f32 v26, v70, v26, v71
	s_cmp_eq_u32 s99, 12
	s_cbranch_scc0 .Lcf_skip_0_12
	s_add_u32 s100, s68, 0x16278c40
	s_addc_u32 s101, s69, 0
	global_store_dword v21, v26, s[100:101]
.Lcf_skip_0_12:
	v_fma_f32 v26, v78, v26, v79
	s_cmp_eq_u32 s99, 13
	s_cbranch_scc0 .Lcf_skip_0_13
	s_add_u32 s100, s68, 0x16279c40
	s_addc_u32 s101, s69, 0
	global_store_dword v21, v26, s[100:101]
.Lcf_skip_0_13:
	v_fma_f32 v26, v80, v26, v81
	s_cmp_eq_u32 s99, 14
	s_cbranch_scc0 .Lcf_skip_0_14
	s_add_u32 s100, s68, 0x1627ac40
	s_addc_u32 s101, s69, 0
	global_store_dword v21, v26, s[100:101]
.Lcf_skip_0_14:
	v_fma_f32 v26, v82, v26, v83
	s_cmp_eq_u32 s99, 15
	s_cbranch_scc0 .Lcf_skip_0_15
	s_add_u32 s100, s68, 0x1627bc40
	s_addc_u32 s101, s69, 0
	global_store_dword v21, v26, s[100:101]
.Lcf_skip_0_15:
	v_fma_f32 v26, v84, v26, v85
	s_cmp_eq_u32 s99, 0
	s_cbranch_scc0 .Lcf_skip_0_16
	s_add_u32 s100, s68, 0x1627cc40
	s_addc_u32 s101, s69, 0
	global_store_dword v21, v26, s[100:101]
.Lcf_skip_0_16:
	v_fma_f32 v26, v86, v26, v87
	s_cmp_eq_u32 s99, 1
	s_cbranch_scc0 .Lcf_skip_0_17
	s_add_u32 s100, s68, 0x1627dc40
	s_addc_u32 s101, s69, 0
	global_store_dword v21, v26, s[100:101]
.Lcf_skip_0_17:
	v_fma_f32 v26, v88, v26, v89
	s_cmp_eq_u32 s99, 2
	s_cbranch_scc0 .Lcf_skip_0_18
	s_add_u32 s100, s68, 0x1627ec40
	s_addc_u32 s101, s69, 0
	global_store_dword v21, v26, s[100:101]
.Lcf_skip_0_18:
	v_fma_f32 v26, v90, v26, v91
	s_cmp_eq_u32 s99, 3
	s_cbranch_scc0 .Lcf_skip_0_19
	s_add_u32 s100, s68, 0x1627fc40
	s_addc_u32 s101, s69, 0
	global_store_dword v21, v26, s[100:101]
.Lcf_skip_0_19:
	v_fma_f32 v26, v92, v26, v93
	s_cmp_eq_u32 s99, 4
	s_cbranch_scc0 .Lcf_skip_0_20
	s_add_u32 s100, s68, 0x16280c40
	s_addc_u32 s101, s69, 0
	global_store_dword v21, v26, s[100:101]
.Lcf_skip_0_20:
	v_fma_f32 v26, v94, v26, v95
	s_cmp_eq_u32 s99, 5
	s_cbranch_scc0 .Lcf_skip_0_21
	s_add_u32 s100, s68, 0x16281c40
	s_addc_u32 s101, s69, 0
	global_store_dword v21, v26, s[100:101]
.Lcf_skip_0_21:
	v_fma_f32 v26, v96, v26, v97
	s_cmp_eq_u32 s99, 6
	s_cbranch_scc0 .Lcf_skip_0_22
	s_add_u32 s100, s68, 0x16282c40
	s_addc_u32 s101, s69, 0
	global_store_dword v21, v26, s[100:101]
.Lcf_skip_0_22:
	v_fma_f32 v26, v98, v26, v99
	s_cmp_eq_u32 s99, 7
	s_cbranch_scc0 .Lcf_skip_0_23
	s_add_u32 s100, s68, 0x16283c40
	s_addc_u32 s101, s69, 0
	global_store_dword v21, v26, s[100:101]
.Lcf_skip_0_23:
	v_fma_f32 v26, v100, v26, v101
	s_cmp_eq_u32 s99, 8
	s_cbranch_scc0 .Lcf_skip_0_24
	s_add_u32 s100, s68, 0x16284c40
	s_addc_u32 s101, s69, 0
	global_store_dword v21, v26, s[100:101]
.Lcf_skip_0_24:
	v_fma_f32 v26, v102, v26, v103
	s_cmp_eq_u32 s99, 9
	s_cbranch_scc0 .Lcf_skip_0_25
	s_add_u32 s100, s68, 0x16285c40
	s_addc_u32 s101, s69, 0
	global_store_dword v21, v26, s[100:101]
.Lcf_skip_0_25:
	v_fma_f32 v26, v104, v26, v105
	s_cmp_eq_u32 s99, 10
	s_cbranch_scc0 .Lcf_skip_0_26
	s_add_u32 s100, s68, 0x16286c40
	s_addc_u32 s101, s69, 0
	global_store_dword v21, v26, s[100:101]
.Lcf_skip_0_26:
	v_fma_f32 v26, v106, v26, v107
	s_cmp_eq_u32 s99, 11
	s_cbranch_scc0 .Lcf_skip_0_27
	s_add_u32 s100, s68, 0x16287c40
	s_addc_u32 s101, s69, 0
	global_store_dword v21, v26, s[100:101]
.Lcf_skip_0_27:
	v_fma_f32 v26, v108, v26, v109
	s_cmp_eq_u32 s99, 12
	s_cbranch_scc0 .Lcf_skip_0_28
	s_add_u32 s100, s68, 0x16288c40
	s_addc_u32 s101, s69, 0
	global_store_dword v21, v26, s[100:101]
.Lcf_skip_0_28:
	v_fma_f32 v26, v110, v26, v111
	s_cmp_eq_u32 s99, 13
	s_cbranch_scc0 .Lcf_skip_0_29
	s_add_u32 s100, s68, 0x16289c40
	s_addc_u32 s101, s69, 0
	global_store_dword v21, v26, s[100:101]
.Lcf_skip_0_29:
	v_fma_f32 v26, v112, v26, v113
	s_cmp_eq_u32 s99, 14
	s_cbranch_scc0 .Lcf_skip_0_30
	s_add_u32 s100, s68, 0x1628ac40
	s_addc_u32 s101, s69, 0
	global_store_dword v21, v26, s[100:101]
.Lcf_skip_0_30:
	v_fma_f32 v26, v114, v26, v115
	s_cmp_eq_u32 s99, 15
	s_cbranch_scc0 .Lcf_skip_0_31
	s_add_u32 s100, s68, 0x1628bc40
	s_addc_u32 s101, s69, 0
	global_store_dword v21, v26, s[100:101]
.Lcf_skip_0_31:
	v_fma_f32 v26, v116, v26, v117
	s_cmp_eq_u32 s99, 0
	s_cbranch_scc0 .Lcf_skip_0_32
	s_add_u32 s100, s68, 0x1628cc40
	s_addc_u32 s101, s69, 0
	global_store_dword v21, v26, s[100:101]
.Lcf_skip_0_32:
	v_fma_f32 v26, v118, v26, v119
	s_branch .Lcf_join
.Lcf_var_1:
	s_add_u32 s100, s68, 0x160a6c40
	s_addc_u32 s101, s69, 0
	global_load_dwordx2 v[48:49], v20, s[100:101]
	s_add_u32 s100, s68, 0x160a8c40
	s_addc_u32 s101, s69, 0
	global_load_dwordx2 v[50:51], v20, s[100:101]
	s_add_u32 s100, s68, 0x160aac40
	s_addc_u32 s101, s69, 0
	global_load_dwordx2 v[52:53], v20, s[100:101]
	s_add_u32 s100, s68, 0x160acc40
	s_addc_u32 s101, s69, 0
	global_load_dwordx2 v[54:55], v20, s[100:101]
	s_add_u32 s100, s68, 0x160aec40
	s_addc_u32 s101, s69, 0
	global_load_dwordx2 v[56:57], v20, s[100:101]
	s_add_u32 s100, s68, 0x160b0c40
	s_addc_u32 s101, s69, 0
	global_load_dwordx2 v[58:59], v20, s[100:101]
	s_add_u32 s100, s68, 0x160b2c40
	s_addc_u32 s101, s69, 0
	global_load_dwordx2 v[60:61], v20, s[100:101]
	s_add_u32 s100, s68, 0x160b4c40
	s_addc_u32 s101, s69, 0
	global_load_dwordx2 v[62:63], v20, s[100:101]
	s_add_u32 s100, s68, 0x160b6c40
	s_addc_u32 s101, s69, 0
	global_load_dwordx2 v[64:65], v20, s[100:101]
	s_add_u32 s100, s68, 0x160b8c40
	s_addc_u32 s101, s69, 0
	global_load_dwordx2 v[66:67], v20, s[100:101]
	s_add_u32 s100, s68, 0x160bac40
	s_addc_u32 s101, s69, 0
	global_load_dwordx2 v[68:69], v20, s[100:101]
	s_add_u32 s100, s68, 0x160bcc40
	s_addc_u32 s101, s69, 0
	global_load_dwordx2 v[70:71], v20, s[100:101]
	s_add_u32 s100, s68, 0x160bec40
	s_addc_u32 s101, s69, 0
	global_load_dwordx2 v[78:79], v20, s[100:101]
	s_add_u32 s100, s68, 0x160c0c40
	s_addc_u32 s101, s69, 0
	global_load_dwordx2 v[80:81], v20, s[100:101]
	s_add_u32 s100, s68, 0x160c2c40
	s_addc_u32 s101, s69, 0
	global_load_dwordx2 v[82:83], v20, s[100:101]
	s_add_u32 s100, s68, 0x160c4c40
	s_addc_u32 s101, s69, 0
	global_load_dwordx2 v[84:85], v20, s[100:101]
	s_add_u32 s100, s68, 0x160c6c40
	s_addc_u32 s101, s69, 0
	global_load_dwordx2 v[86:87], v20, s[100:101]
	s_add_u32 s100, s68, 0x160c8c40
	s_addc_u32 s101, s69, 0
	global_load_dwordx2 v[88:89], v20, s[100:101]
	s_add_u32 s100, s68, 0x160cac40
	s_addc_u32 s101, s69, 0
	global_load_dwordx2 v[90:91], v20, s[100:101]
	s_add_u32 s100, s68, 0x160ccc40
	s_addc_u32 s101, s69, 0
	global_load_dwordx2 v[92:93], v20, s[100:101]
	s_add_u32 s100, s68, 0x160cec40
	s_addc_u32 s101, s69, 0
	global_load_dwordx2 v[94:95], v20, s[100:101]
	s_add_u32 s100, s68, 0x160d0c40
	s_addc_u32 s101, s69, 0
	global_load_dwordx2 v[96:97], v20, s[100:101]
	s_add_u32 s100, s68, 0x160d2c40
	s_addc_u32 s101, s69, 0
	global_load_dwordx2 v[98:99], v20, s[100:101]
	s_add_u32 s100, s68, 0x160d4c40
	s_addc_u32 s101, s69, 0
	global_load_dwordx2 v[100:101], v20, s[100:101]
	s_add_u32 s100, s68, 0x160d6c40
	s_addc_u32 s101, s69, 0
	global_load_dwordx2 v[102:103], v20, s[100:101]
	s_add_u32 s100, s68, 0x160d8c40
	s_addc_u32 s101, s69, 0
	global_load_dwordx2 v[104:105], v20, s[100:101]
	s_add_u32 s100, s68, 0x160dac40
	s_addc_u32 s101, s69, 0
	global_load_dwordx2 v[106:107], v20, s[100:101]
	s_add_u32 s100, s68, 0x160dcc40
	s_addc_u32 s101, s69, 0
	global_load_dwordx2 v[108:109], v20, s[100:101]
	s_add_u32 s100, s68, 0x160dec40
	s_addc_u32 s101, s69, 0
	global_load_dwordx2 v[110:111], v20, s[100:101]
	s_add_u32 s100, s68, 0x160e0c40
	s_addc_u32 s101, s69, 0
	global_load_dwordx2 v[112:113], v20, s[100:101]
	s_add_u32 s100, s68, 0x160e2c40
	s_addc_u32 s101, s69, 0
	global_load_dwordx2 v[114:115], v20, s[100:101]
	s_add_u32 s100, s68, 0x160e4c40
	s_addc_u32 s101, s69, 0
	global_load_dwordx2 v[116:117], v20, s[100:101]
	s_add_u32 s100, s68, 0x160e6c40
	s_addc_u32 s101, s69, 0
	global_load_dwordx2 v[118:119], v20, s[100:101]
	v_mov_b32_e32 v24, 1.0
	v_mov_b32_e32 v25, 0
	s_waitcnt vmcnt(32)
	v_fma_f32 v25, v48, v25, v49
	v_mul_f32_e32 v24, v24, v48
	s_waitcnt vmcnt(31)
	v_fma_f32 v25, v50, v25, v51
	v_mul_f32_e32 v24, v24, v50
	s_waitcnt vmcnt(30)
	v_fma_f32 v25, v52, v25, v53
	v_mul_f32_e32 v24, v24, v52
	s_waitcnt vmcnt(29)
	v_fma_f32 v25, v54, v25, v55
	v_mul_f32_e32 v24, v24, v54
	s_waitcnt vmcnt(28)
	v_fma_f32 v25, v56, v25, v57
	v_mul_f32_e32 v24, v24, v56
	s_waitcnt vmcnt(27)
	v_fma_f32 v25, v58, v25, v59
	v_mul_f32_e32 v24, v24, v58
	s_waitcnt vmcnt(26)
	v_fma_f32 v25, v60, v25, v61
	v_mul_f32_e32 v24, v24, v60
	s_waitcnt vmcnt(25)
	v_fma_f32 v25, v62, v25, v63
	v_mul_f32_e32 v24, v24, v62
	s_waitcnt vmcnt(24)
	v_fma_f32 v25, v64, v25, v65
	v_mul_f32_e32 v24, v24, v64
	s_waitcnt vmcnt(23)
	v_fma_f32 v25, v66, v25, v67
	v_mul_f32_e32 v24, v24, v66
	s_waitcnt vmcnt(22)
	v_fma_f32 v25, v68, v25, v69
	v_mul_f32_e32 v24, v24, v68
	s_waitcnt vmcnt(21)
	v_fma_f32 v25, v70, v25, v71
	v_mul_f32_e32 v24, v24, v70
	s_waitcnt vmcnt(20)
	v_fma_f32 v25, v78, v25, v79
	v_mul_f32_e32 v24, v24, v78
	s_waitcnt vmcnt(19)
	v_fma_f32 v25, v80, v25, v81
	v_mul_f32_e32 v24, v24, v80
	s_waitcnt vmcnt(18)
	v_fma_f32 v25, v82, v25, v83
	v_mul_f32_e32 v24, v24, v82
	s_waitcnt vmcnt(17)
	v_fma_f32 v25, v84, v25, v85
	v_mul_f32_e32 v24, v24, v84
	s_waitcnt vmcnt(16)
	v_fma_f32 v25, v86, v25, v87
	v_mul_f32_e32 v24, v24, v86
	s_waitcnt vmcnt(15)
	v_fma_f32 v25, v88, v25, v89
	v_mul_f32_e32 v24, v24, v88
	s_waitcnt vmcnt(14)
	v_fma_f32 v25, v90, v25, v91
	v_mul_f32_e32 v24, v24, v90
	s_waitcnt vmcnt(13)
	v_fma_f32 v25, v92, v25, v93
	v_mul_f32_e32 v24, v24, v92
	s_waitcnt vmcnt(12)
	v_fma_f32 v25, v94, v25, v95
	v_mul_f32_e32 v24, v24, v94
	s_waitcnt vmcnt(11)
	v_fma_f32 v25, v96, v25, v97
	v_mul_f32_e32 v24, v24, v96
	s_waitcnt vmcnt(10)
	v_fma_f32 v25, v98, v25, v99
	v_mul_f32_e32 v24, v24, v98
	s_waitcnt vmcnt(9)
	v_fma_f32 v25, v100, v25, v101
	v_mul_f32_e32 v24, v24, v100
	s_waitcnt vmcnt(8)
	v_fma_f32 v25, v102, v25, v103
	v_mul_f32_e32 v24, v24, v102
	s_waitcnt vmcnt(7)
	v_fma_f32 v25, v104, v25, v105
	v_mul_f32_e32 v24, v24, v104
	s_waitcnt vmcnt(6)
	v_fma_f32 v25, v106, v25, v107
	v_mul_f32_e32 v24, v24, v106
	s_waitcnt vmcnt(5)
	v_fma_f32 v25, v108, v25, v109
	v_mul_f32_e32 v24, v24, v108
	s_waitcnt vmcnt(4)
	v_fma_f32 v25, v110, v25, v111
	v_mul_f32_e32 v24, v24, v110
	s_waitcnt vmcnt(3)
	v_fma_f32 v25, v112, v25, v113
	v_mul_f32_e32 v24, v24, v112
	s_waitcnt vmcnt(2)
	v_fma_f32 v25, v114, v25, v115
	v_mul_f32_e32 v24, v24, v114
	s_waitcnt vmcnt(1)
	v_fma_f32 v25, v116, v25, v117
	v_mul_f32_e32 v24, v24, v116
	s_waitcnt vmcnt(0)
	v_fma_f32 v25, v118, v25, v119
	v_mul_f32_e32 v24, v24, v118
	ds_write_b64 v22, v[24:25] offset:512
	s_waitcnt lgkmcnt(0)
	s_barrier
	v_mov_b32_e32 v26, 0
	ds_read_b64 v[28:29], v22 offset:0
	s_waitcnt lgkmcnt(0)
	v_fma_f32 v26, v28, v26, v29
	s_cmp_eq_u32 s99, 1
	s_cbranch_scc0 .Lcf_skip_1_0
	s_add_u32 s100, s68, 0x1628dc40
	s_addc_u32 s101, s69, 0
	global_store_dword v21, v26, s[100:101]
.Lcf_skip_1_0:
	v_fma_f32 v26, v48, v26, v49
	s_cmp_eq_u32 s99, 2
	s_cbranch_scc0 .Lcf_skip_1_1
	s_add_u32 s100, s68, 0x1628ec40
	s_addc_u32 s101, s69, 0
	global_store_dword v21, v26, s[100:101]
.Lcf_skip_1_1:
	v_fma_f32 v26, v50, v26, v51
	s_cmp_eq_u32 s99, 3
	s_cbranch_scc0 .Lcf_skip_1_2
	s_add_u32 s100, s68, 0x1628fc40
	s_addc_u32 s101, s69, 0
	global_store_dword v21, v26, s[100:101]
.Lcf_skip_1_2:
	v_fma_f32 v26, v52, v26, v53
	s_cmp_eq_u32 s99, 4
	s_cbranch_scc0 .Lcf_skip_1_3
	s_add_u32 s100, s68, 0x16290c40
	s_addc_u32 s101, s69, 0
	global_store_dword v21, v26, s[100:101]
.Lcf_skip_1_3:
	v_fma_f32 v26, v54, v26, v55
	s_cmp_eq_u32 s99, 5
	s_cbranch_scc0 .Lcf_skip_1_4
	s_add_u32 s100, s68, 0x16291c40
	s_addc_u32 s101, s69, 0
	global_store_dword v21, v26, s[100:101]
.Lcf_skip_1_4:
	v_fma_f32 v26, v56, v26, v57
	s_cmp_eq_u32 s99, 6
	s_cbranch_scc0 .Lcf_skip_1_5
	s_add_u32 s100, s68, 0x16292c40
	s_addc_u32 s101, s69, 0
	global_store_dword v21, v26, s[100:101]
.Lcf_skip_1_5:
	v_fma_f32 v26, v58, v26, v59
	s_cmp_eq_u32 s99, 7
	s_cbranch_scc0 .Lcf_skip_1_6
	s_add_u32 s100, s68, 0x16293c40
	s_addc_u32 s101, s69, 0
	global_store_dword v21, v26, s[100:101]
.Lcf_skip_1_6:
	v_fma_f32 v26, v60, v26, v61
	s_cmp_eq_u32 s99, 8
	s_cbranch_scc0 .Lcf_skip_1_7
	s_add_u32 s100, s68, 0x16294c40
	s_addc_u32 s101, s69, 0
	global_store_dword v21, v26, s[100:101]
.Lcf_skip_1_7:
	v_fma_f32 v26, v62, v26, v63
	s_cmp_eq_u32 s99, 9
	s_cbranch_scc0 .Lcf_skip_1_8
	s_add_u32 s100, s68, 0x16295c40
	s_addc_u32 s101, s69, 0
	global_store_dword v21, v26, s[100:101]
.Lcf_skip_1_8:
	v_fma_f32 v26, v64, v26, v65
	s_cmp_eq_u32 s99, 10
	s_cbranch_scc0 .Lcf_skip_1_9
	s_add_u32 s100, s68, 0x16296c40
	s_addc_u32 s101, s69, 0
	global_store_dword v21, v26, s[100:101]
.Lcf_skip_1_9:
	v_fma_f32 v26, v66, v26, v67
	s_cmp_eq_u32 s99, 11
	s_cbranch_scc0 .Lcf_skip_1_10
	s_add_u32 s100, s68, 0x16297c40
	s_addc_u32 s101, s69, 0
	global_store_dword v21, v26, s[100:101]
.Lcf_skip_1_10:
	v_fma_f32 v26, v68, v26, v69
	s_cmp_eq_u32 s99, 12
	s_cbranch_scc0 .Lcf_skip_1_11
	s_add_u32 s100, s68, 0x16298c40
	s_addc_u32 s101, s69, 0
	global_store_dword v21, v26, s[100:101]
.Lcf_skip_1_11:
	v_fma_f32 v26, v70, v26, v71
	s_cmp_eq_u32 s99, 13
	s_cbranch_scc0 .Lcf_skip_1_12
	s_add_u32 s100, s68, 0x16299c40
	s_addc_u32 s101, s69, 0
	global_store_dword v21, v26, s[100:101]
.Lcf_skip_1_12:
	v_fma_f32 v26, v78, v26, v79
	s_cmp_eq_u32 s99, 14
	s_cbranch_scc0 .Lcf_skip_1_13
	s_add_u32 s100, s68, 0x1629ac40
	s_addc_u32 s101, s69, 0
	global_store_dword v21, v26, s[100:101]
.Lcf_skip_1_13:
	v_fma_f32 v26, v80, v26, v81
	s_cmp_eq_u32 s99, 15
	s_cbranch_scc0 .Lcf_skip_1_14
	s_add_u32 s100, s68, 0x1629bc40
	s_addc_u32 s101, s69, 0
	global_store_dword v21, v26, s[100:101]
.Lcf_skip_1_14:
	v_fma_f32 v26, v82, v26, v83
	s_cmp_eq_u32 s99, 0
	s_cbranch_scc0 .Lcf_skip_1_15
	s_add_u32 s100, s68, 0x1629cc40
	s_addc_u32 s101, s69, 0
	global_store_dword v21, v26, s[100:101]
.Lcf_skip_1_15:
	v_fma_f32 v26, v84, v26, v85
	s_cmp_eq_u32 s99, 1
	s_cbranch_scc0 .Lcf_skip_1_16
	s_add_u32 s100, s68, 0x1629dc40
	s_addc_u32 s101, s69, 0
	global_store_dword v21, v26, s[100:101]
.Lcf_skip_1_16:
	v_fma_f32 v26, v86, v26, v87
	s_cmp_eq_u32 s99, 2
	s_cbranch_scc0 .Lcf_skip_1_17
	s_add_u32 s100, s68, 0x1629ec40
	s_addc_u32 s101, s69, 0
	global_store_dword v21, v26, s[100:101]
.Lcf_skip_1_17:
	v_fma_f32 v26, v88, v26, v89
	s_cmp_eq_u32 s99, 3
	s_cbranch_scc0 .Lcf_skip_1_18
	s_add_u32 s100, s68, 0x1629fc40
	s_addc_u32 s101, s69, 0
	global_store_dword v21, v26, s[100:101]
.Lcf_skip_1_18:
	v_fma_f32 v26, v90, v26, v91
	s_cmp_eq_u32 s99, 4
	s_cbranch_scc0 .Lcf_skip_1_19
	s_add_u32 s100, s68, 0x162a0c40
	s_addc_u32 s101, s69, 0
	global_store_dword v21, v26, s[100:101]
.Lcf_skip_1_19:
	v_fma_f32 v26, v92, v26, v93
	s_cmp_eq_u32 s99, 5
	s_cbranch_scc0 .Lcf_skip_1_20
	s_add_u32 s100, s68, 0x162a1c40
	s_addc_u32 s101, s69, 0
	global_store_dword v21, v26, s[100:101]
.Lcf_skip_1_20:
	v_fma_f32 v26, v94, v26, v95
	s_cmp_eq_u32 s99, 6
	s_cbranch_scc0 .Lcf_skip_1_21
	s_add_u32 s100, s68, 0x162a2c40
	s_addc_u32 s101, s69, 0
	global_store_dword v21, v26, s[100:101]
.Lcf_skip_1_21:
	v_fma_f32 v26, v96, v26, v97
	s_cmp_eq_u32 s99, 7
	s_cbranch_scc0 .Lcf_skip_1_22
	s_add_u32 s100, s68, 0x162a3c40
	s_addc_u32 s101, s69, 0
	global_store_dword v21, v26, s[100:101]
.Lcf_skip_1_22:
	v_fma_f32 v26, v98, v26, v99
	s_cmp_eq_u32 s99, 8
	s_cbranch_scc0 .Lcf_skip_1_23
	s_add_u32 s100, s68, 0x162a4c40
	s_addc_u32 s101, s69, 0
	global_store_dword v21, v26, s[100:101]
.Lcf_skip_1_23:
	v_fma_f32 v26, v100, v26, v101
	s_cmp_eq_u32 s99, 9
	s_cbranch_scc0 .Lcf_skip_1_24
	s_add_u32 s100, s68, 0x162a5c40
	s_addc_u32 s101, s69, 0
	global_store_dword v21, v26, s[100:101]
.Lcf_skip_1_24:
	v_fma_f32 v26, v102, v26, v103
	s_cmp_eq_u32 s99, 10
	s_cbranch_scc0 .Lcf_skip_1_25
	s_add_u32 s100, s68, 0x162a6c40
	s_addc_u32 s101, s69, 0
	global_store_dword v21, v26, s[100:101]
.Lcf_skip_1_25:
	v_fma_f32 v26, v104, v26, v105
	s_cmp_eq_u32 s99, 11
	s_cbranch_scc0 .Lcf_skip_1_26
	s_add_u32 s100, s68, 0x162a7c40
	s_addc_u32 s101, s69, 0
	global_store_dword v21, v26, s[100:101]
.Lcf_skip_1_26:
	v_fma_f32 v26, v106, v26, v107
	s_cmp_eq_u32 s99, 12
	s_cbranch_scc0 .Lcf_skip_1_27
	s_add_u32 s100, s68, 0x162a8c40
	s_addc_u32 s101, s69, 0
	global_store_dword v21, v26, s[100:101]
.Lcf_skip_1_27:
	v_fma_f32 v26, v108, v26, v109
	s_cmp_eq_u32 s99, 13
	s_cbranch_scc0 .Lcf_skip_1_28
	s_add_u32 s100, s68, 0x162a9c40
	s_addc_u32 s101, s69, 0
	global_store_dword v21, v26, s[100:101]
.Lcf_skip_1_28:
	v_fma_f32 v26, v110, v26, v111
	s_cmp_eq_u32 s99, 14
	s_cbranch_scc0 .Lcf_skip_1_29
	s_add_u32 s100, s68, 0x162aac40
	s_addc_u32 s101, s69, 0
	global_store_dword v21, v26, s[100:101]
.Lcf_skip_1_29:
	v_fma_f32 v26, v112, v26, v113
	s_cmp_eq_u32 s99, 15
	s_cbranch_scc0 .Lcf_skip_1_30
	s_add_u32 s100, s68, 0x162abc40
	s_addc_u32 s101, s69, 0
	global_store_dword v21, v26, s[100:101]
.Lcf_skip_1_30:
	v_fma_f32 v26, v114, v26, v115
	s_cmp_eq_u32 s99, 0
	s_cbranch_scc0 .Lcf_skip_1_31
	s_add_u32 s100, s68, 0x162acc40
	s_addc_u32 s101, s69, 0
	global_store_dword v21, v26, s[100:101]
.Lcf_skip_1_31:
	v_fma_f32 v26, v116, v26, v117
	s_cmp_eq_u32 s99, 1
	s_cbranch_scc0 .Lcf_skip_1_32
	s_add_u32 s100, s68, 0x162adc40
	s_addc_u32 s101, s69, 0
	global_store_dword v21, v26, s[100:101]

.Lcf_var_2:
	s_add_u32 s100, s68, 0x160e8c40
	s_addc_u32 s101, s69, 0
	global_load_dwordx2 v[48:49], v20, s[100:101]
	s_add_u32 s100, s68, 0x160eac40
	s_addc_u32 s101, s69, 0
	global_load_dwordx2 v[50:51], v20, s[100:101]
	s_add_u32 s100, s68, 0x160ecc40
	s_addc_u32 s101, s69, 0
	global_load_dwordx2 v[52:53], v20, s[100:101]
	s_add_u32 s100, s68, 0x160eec40
	s_addc_u32 s101, s69, 0
	global_load_dwordx2 v[54:55], v20, s[100:101]
	s_add_u32 s100, s68, 0x160f0c40
	s_addc_u32 s101, s69, 0
	global_load_dwordx2 v[56:57], v20, s[100:101]
	s_add_u32 s100, s68, 0x160f2c40
	s_addc_u32 s101, s69, 0
	global_load_dwordx2 v[58:59], v20, s[100:101]
	s_add_u32 s100, s68, 0x160f4c40
	s_addc_u32 s101, s69, 0
	global_load_dwordx2 v[60:61], v20, s[100:101]
	s_add_u32 s100, s68, 0x160f6c40
	s_addc_u32 s101, s69, 0
	global_load_dwordx2 v[62:63], v20, s[100:101]
	s_add_u32 s100, s68, 0x160f8c40
	s_addc_u32 s101, s69, 0
	global_load_dwordx2 v[64:65], v20, s[100:101]
	s_add_u32 s100, s68, 0x160fac40
	s_addc_u32 s101, s69, 0
	global_load_dwordx2 v[66:67], v20, s[100:101]
	s_add_u32 s100, s68, 0x160fcc40
	s_addc_u32 s101, s69, 0
	global_load_dwordx2 v[68:69], v20, s[100:101]
	s_add_u32 s100, s68, 0x160fec40
	s_addc_u32 s101, s69, 0
	global_load_dwordx2 v[70:71], v20, s[100:101]
	s_add_u32 s100, s68, 0x16100c40
	s_addc_u32 s101, s69, 0
	global_load_dwordx2 v[78:79], v20, s[100:101]
	s_add_u32 s100, s68, 0x16102c40
	s_addc_u32 s101, s69, 0
	global_load_dwordx2 v[80:81], v20, s[100:101]
	s_add_u32 s100, s68, 0x16104c40
	s_addc_u32 s101, s69, 0
	global_load_dwordx2 v[82:83], v20, s[100:101]
	s_add_u32 s100, s68, 0x16106c40
	s_addc_u32 s101, s69, 0
	global_load_dwordx2 v[84:85], v20, s[100:101]
	s_add_u32 s100, s68, 0x16108c40
	s_addc_u32 s101, s69, 0
	global_load_dwordx2 v[86:87], v20, s[100:101]
	s_add_u32 s100, s68, 0x1610ac40
	s_addc_u32 s101, s69, 0
	global_load_dwordx2 v[88:89], v20, s[100:101]
	s_add_u32 s100, s68, 0x1610cc40
	s_addc_u32 s101, s69, 0
	global_load_dwordx2 v[90:91], v20, s[100:101]
	s_add_u32 s100, s68, 0x1610ec40
	s_addc_u32 s101, s69, 0
	global_load_dwordx2 v[92:93], v20, s[100:101]
	s_add_u32 s100, s68, 0x16110c40
	s_addc_u32 s101, s69, 0
	global_load_dwordx2 v[94:95], v20, s[100:101]
	s_add_u32 s100, s68, 0x16112c40
	s_addc_u32 s101, s69, 0
	global_load_dwordx2 v[96:97], v20, s[100:101]
	s_add_u32 s100, s68, 0x16114c40
	s_addc_u32 s101, s69, 0
	global_load_dwordx2 v[98:99], v20, s[100:101]
	s_add_u32 s100, s68, 0x16116c40
	s_addc_u32 s101, s69, 0
	global_load_dwordx2 v[100:101], v20, s[100:101]
	s_add_u32 s100, s68, 0x16118c40
	s_addc_u32 s101, s69, 0
	global_load_dwordx2 v[102:103], v20, s[100:101]
	s_add_u32 s100, s68, 0x1611ac40
	s_addc_u32 s101, s69, 0
	global_load_dwordx2 v[104:105], v20, s[100:101]
	s_add_u32 s100, s68, 0x1611cc40
	s_addc_u32 s101, s69, 0
	global_load_dwordx2 v[106:107], v20, s[100:101]
	s_add_u32 s100, s68, 0x1611ec40
	s_addc_u32 s101, s69, 0
	global_load_dwordx2 v[108:109], v20, s[100:101]
	s_add_u32 s100, s68, 0x16120c40
	s_addc_u32 s101, s69, 0
	global_load_dwordx2 v[110:111], v20, s[100:101]
	s_add_u32 s100, s68, 0x16122c40
	s_addc_u32 s101, s69, 0
	global_load_dwordx2 v[112:113], v20, s[100:101]
	s_add_u32 s100, s68, 0x16124c40
	s_addc_u32 s101, s69, 0
	global_load_dwordx2 v[114:115], v20, s[100:101]
	s_add_u32 s100, s68, 0x16126c40
	s_addc_u32 s101, s69, 0
	global_load_dwordx2 v[116:117], v20, s[100:101]
	s_add_u32 s100, s68, 0x16128c40
	s_addc_u32 s101, s69, 0
	global_load_dwordx2 v[118:119], v20, s[100:101]
	v_mov_b32_e32 v24, 1.0
	v_mov_b32_e32 v25, 0
	s_waitcnt vmcnt(32)
	v_fma_f32 v25, v48, v25, v49
	v_mul_f32_e32 v24, v24, v48
	s_waitcnt vmcnt(31)
	v_fma_f32 v25, v50, v25, v51
	v_mul_f32_e32 v24, v24, v50
	s_waitcnt vmcnt(30)
	v_fma_f32 v25, v52, v25, v53
	v_mul_f32_e32 v24, v24, v52
	s_waitcnt vmcnt(29)
	v_fma_f32 v25, v54, v25, v55
	v_mul_f32_e32 v24, v24, v54
	s_waitcnt vmcnt(28)
	v_fma_f32 v25, v56, v25, v57
	v_mul_f32_e32 v24, v24, v56
	s_waitcnt vmcnt(27)
	v_fma_f32 v25, v58, v25, v59
	v_mul_f32_e32 v24, v24, v58
	s_waitcnt vmcnt(26)
	v_fma_f32 v25, v60, v25, v61
	v_mul_f32_e32 v24, v24, v60
	s_waitcnt vmcnt(25)
	v_fma_f32 v25, v62, v25, v63
	v_mul_f32_e32 v24, v24, v62
	s_waitcnt vmcnt(24)
	v_fma_f32 v25, v64, v25, v65
	v_mul_f32_e32 v24, v24, v64
	s_waitcnt vmcnt(23)
	v_fma_f32 v25, v66, v25, v67
	v_mul_f32_e32 v24, v24, v66
	s_waitcnt vmcnt(22)
	v_fma_f32 v25, v68, v25, v69
	v_mul_f32_e32 v24, v24, v68
	s_waitcnt vmcnt(21)
	v_fma_f32 v25, v70, v25, v71
	v_mul_f32_e32 v24, v24, v70
	s_waitcnt vmcnt(20)
	v_fma_f32 v25, v78, v25, v79
	v_mul_f32_e32 v24, v24, v78
	s_waitcnt vmcnt(19)
	v_fma_f32 v25, v80, v25, v81
	v_mul_f32_e32 v24, v24, v80
	s_waitcnt vmcnt(18)
	v_fma_f32 v25, v82, v25, v83
	v_mul_f32_e32 v24, v24, v82
	s_waitcnt vmcnt(17)
	v_fma_f32 v25, v84, v25, v85
	v_mul_f32_e32 v24, v24, v84
	s_waitcnt vmcnt(16)
	v_fma_f32 v25, v86, v25, v87
	v_mul_f32_e32 v24, v24, v86
	s_waitcnt vmcnt(15)
	v_fma_f32 v25, v88, v25, v89
	v_mul_f32_e32 v24, v24, v88
	s_waitcnt vmcnt(14)
	v_fma_f32 v25, v90, v25, v91
	v_mul_f32_e32 v24, v24, v90
	s_waitcnt vmcnt(13)
	v_fma_f32 v25, v92, v25, v93
	v_mul_f32_e32 v24, v24, v92
	s_waitcnt vmcnt(12)
	v_fma_f32 v25, v94, v25, v95
	v_mul_f32_e32 v24, v24, v94
	s_waitcnt vmcnt(11)
	v_fma_f32 v25, v96, v25, v97
	v_mul_f32_e32 v24, v24, v96
	s_waitcnt vmcnt(10)
	v_fma_f32 v25, v98, v25, v99
	v_mul_f32_e32 v24, v24, v98
	s_waitcnt vmcnt(9)
	v_fma_f32 v25, v100, v25, v101
	v_mul_f32_e32 v24, v24, v100
	s_waitcnt vmcnt(8)
	v_fma_f32 v25, v102, v25, v103
	v_mul_f32_e32 v24, v24, v102
	s_waitcnt vmcnt(7)
	v_fma_f32 v25, v104, v25, v105
	v_mul_f32_e32 v24, v24, v104
	s_waitcnt vmcnt(6)
	v_fma_f32 v25, v106, v25, v107
	v_mul_f32_e32 v24, v24, v106
	s_waitcnt vmcnt(5)
	v_fma_f32 v25, v108, v25, v109
	v_mul_f32_e32 v24, v24, v108
	s_waitcnt vmcnt(4)
	v_fma_f32 v25, v110, v25, v111
	v_mul_f32_e32 v24, v24, v110
	s_waitcnt vmcnt(3)
	v_fma_f32 v25, v112, v25, v113
	v_mul_f32_e32 v24, v24, v112
	s_waitcnt vmcnt(2)
	v_fma_f32 v25, v114, v25, v115
	v_mul_f32_e32 v24, v24, v114
	s_waitcnt vmcnt(1)
	v_fma_f32 v25, v116, v25, v117
	v_mul_f32_e32 v24, v24, v116
	s_waitcnt vmcnt(0)
	v_fma_f32 v25, v118, v25, v119
	v_mul_f32_e32 v24, v24, v118
	ds_write_b64 v22, v[24:25] offset:1024
	s_waitcnt lgkmcnt(0)
	s_barrier
	v_mov_b32_e32 v26, 0
	ds_read_b64 v[28:29], v22 offset:0
	s_waitcnt lgkmcnt(0)
	v_fma_f32 v26, v28, v26, v29
	ds_read_b64 v[28:29], v22 offset:512
	s_waitcnt lgkmcnt(0)
	v_fma_f32 v26, v28, v26, v29
	s_cmp_eq_u32 s99, 2
	s_cbranch_scc0 .Lcf_skip_2_0
	s_add_u32 s100, s68, 0x162aec40
	s_addc_u32 s101, s69, 0
	global_store_dword v21, v26, s[100:101]
.Lcf_skip_2_0:
	v_fma_f32 v26, v48, v26, v49
	s_cmp_eq_u32 s99, 3
	s_cbranch_scc0 .Lcf_skip_2_1
	s_add_u32 s100, s68, 0x162afc40
	s_addc_u32 s101, s69, 0
	global_store_dword v21, v26, s[100:101]
.Lcf_skip_2_1:
	v_fma_f32 v26, v50, v26, v51
	s_cmp_eq_u32 s99, 4
	s_cbranch_scc0 .Lcf_skip_2_2
	s_add_u32 s100, s68, 0x162b0c40
	s_addc_u32 s101, s69, 0
	global_store_dword v21, v26, s[100:101]
.Lcf_skip_2_2:
	v_fma_f32 v26, v52, v26, v53
	s_cmp_eq_u32 s99, 5
	s_cbranch_scc0 .Lcf_skip_2_3
	s_add_u32 s100, s68, 0x162b1c40
	s_addc_u32 s101, s69, 0
	global_store_dword v21, v26, s[100:101]
.Lcf_skip_2_3:
	v_fma_f32 v26, v54, v26, v55
	s_cmp_eq_u32 s99, 6
	s_cbranch_scc0 .Lcf_skip_2_4
	s_add_u32 s100, s68, 0x162b2c40
	s_addc_u32 s101, s69, 0
	global_store_dword v21, v26, s[100:101]
.Lcf_skip_2_4:
	v_fma_f32 v26, v56, v26, v57
	s_cmp_eq_u32 s99, 7
	s_cbranch_scc0 .Lcf_skip_2_5
	s_add_u32 s100, s68, 0x162b3c40
	s_addc_u32 s101, s69, 0
	global_store_dword v21, v26, s[100:101]
.Lcf_skip_2_5:
	v_fma_f32 v26, v58, v26, v59
	s_cmp_eq_u32 s99, 8
	s_cbranch_scc0 .Lcf_skip_2_6
	s_add_u32 s100, s68, 0x162b4c40
	s_addc_u32 s101, s69, 0
	global_store_dword v21, v26, s[100:101]
.Lcf_skip_2_6:
	v_fma_f32 v26, v60, v26, v61
	s_cmp_eq_u32 s99, 9
	s_cbranch_scc0 .Lcf_skip_2_7
	s_add_u32 s100, s68, 0x162b5c40
	s_addc_u32 s101, s69, 0
	global_store_dword v21, v26, s[100:101]
.Lcf_skip_2_7:
	v_fma_f32 v26, v62, v26, v63
	s_cmp_eq_u32 s99, 10
	s_cbranch_scc0 .Lcf_skip_2_8
	s_add_u32 s100, s68, 0x162b6c40
	s_addc_u32 s101, s69, 0
	global_store_dword v21, v26, s[100:101]
.Lcf_skip_2_8:
	v_fma_f32 v26, v64, v26, v65
	s_cmp_eq_u32 s99, 11
	s_cbranch_scc0 .Lcf_skip_2_9
	s_add_u32 s100, s68, 0x162b7c40
	s_addc_u32 s101, s69, 0
	global_store_dword v21, v26, s[100:101]
.Lcf_skip_2_9:
	v_fma_f32 v26, v66, v26, v67
	s_cmp_eq_u32 s99, 12
	s_cbranch_scc0 .Lcf_skip_2_10
	s_add_u32 s100, s68, 0x162b8c40
	s_addc_u32 s101, s69, 0
	global_store_dword v21, v26, s[100:101]
.Lcf_skip_2_10:
	v_fma_f32 v26, v68, v26, v69
	s_cmp_eq_u32 s99, 13
	s_cbranch_scc0 .Lcf_skip_2_11
	s_add_u32 s100, s68, 0x162b9c40
	s_addc_u32 s101, s69, 0
	global_store_dword v21, v26, s[100:101]
.Lcf_skip_2_11:
	v_fma_f32 v26, v70, v26, v71
	s_cmp_eq_u32 s99, 14
	s_cbranch_scc0 .Lcf_skip_2_12
	s_add_u32 s100, s68, 0x162bac40
	s_addc_u32 s101, s69, 0
	global_store_dword v21, v26, s[100:101]
.Lcf_skip_2_12:
	v_fma_f32 v26, v78, v26, v79
	s_cmp_eq_u32 s99, 15
	s_cbranch_scc0 .Lcf_skip_2_13
	s_add_u32 s100, s68, 0x162bbc40
	s_addc_u32 s101, s69, 0
	global_store_dword v21, v26, s[100:101]
.Lcf_skip_2_13:
	v_fma_f32 v26, v80, v26, v81
	s_cmp_eq_u32 s99, 0
	s_cbranch_scc0 .Lcf_skip_2_14
	s_add_u32 s100, s68, 0x162bcc40
	s_addc_u32 s101, s69, 0
	global_store_dword v21, v26, s[100:101]
.Lcf_skip_2_14:
	v_fma_f32 v26, v82, v26, v83
	s_cmp_eq_u32 s99, 1
	s_cbranch_scc0 .Lcf_skip_2_15
	s_add_u32 s100, s68, 0x162bdc40
	s_addc_u32 s101, s69, 0
	global_store_dword v21, v26, s[100:101]
.Lcf_skip_2_15:
	v_fma_f32 v26, v84, v26, v85
	s_cmp_eq_u32 s99, 2
	s_cbranch_scc0 .Lcf_skip_2_16
	s_add_u32 s100, s68, 0x162bec40
	s_addc_u32 s101, s69, 0
	global_store_dword v21, v26, s[100:101]
.Lcf_skip_2_16:
	v_fma_f32 v26, v86, v26, v87
	s_cmp_eq_u32 s99, 3
	s_cbranch_scc0 .Lcf_skip_2_17
	s_add_u32 s100, s68, 0x162bfc40
	s_addc_u32 s101, s69, 0
	global_store_dword v21, v26, s[100:101]
.Lcf_skip_2_17:
	v_fma_f32 v26, v88, v26, v89
	s_cmp_eq_u32 s99, 4
	s_cbranch_scc0 .Lcf_skip_2_18
	s_add_u32 s100, s68, 0x162c0c40
	s_addc_u32 s101, s69, 0
	global_store_dword v21, v26, s[100:101]
.Lcf_skip_2_18:
	v_fma_f32 v26, v90, v26, v91
	s_cmp_eq_u32 s99, 5
	s_cbranch_scc0 .Lcf_skip_2_19
	s_add_u32 s100, s68, 0x162c1c40
	s_addc_u32 s101, s69, 0
	global_store_dword v21, v26, s[100:101]
.Lcf_skip_2_19:
	v_fma_f32 v26, v92, v26, v93
	s_cmp_eq_u32 s99, 6
	s_cbranch_scc0 .Lcf_skip_2_20
	s_add_u32 s100, s68, 0x162c2c40
	s_addc_u32 s101, s69, 0
	global_store_dword v21, v26, s[100:101]
.Lcf_skip_2_20:
	v_fma_f32 v26, v94, v26, v95
	s_cmp_eq_u32 s99, 7
	s_cbranch_scc0 .Lcf_skip_2_21
	s_add_u32 s100, s68, 0x162c3c40
	s_addc_u32 s101, s69, 0
	global_store_dword v21, v26, s[100:101]
.Lcf_skip_2_21:
	v_fma_f32 v26, v96, v26, v97
	s_cmp_eq_u32 s99, 8
	s_cbranch_scc0 .Lcf_skip_2_22
	s_add_u32 s100, s68, 0x162c4c40
	s_addc_u32 s101, s69, 0
	global_store_dword v21, v26, s[100:101]
.Lcf_skip_2_22:
	v_fma_f32 v26, v98, v26, v99
	s_cmp_eq_u32 s99, 9
	s_cbranch_scc0 .Lcf_skip_2_23
	s_add_u32 s100, s68, 0x162c5c40
	s_addc_u32 s101, s69, 0
	global_store_dword v21, v26, s[100:101]
.Lcf_skip_2_23:
	v_fma_f32 v26, v100, v26, v101
	s_cmp_eq_u32 s99, 10
	s_cbranch_scc0 .Lcf_skip_2_24
	s_add_u32 s100, s68, 0x162c6c40
	s_addc_u32 s101, s69, 0
	global_store_dword v21, v26, s[100:101]
.Lcf_skip_2_24:
	v_fma_f32 v26, v102, v26, v103
	s_cmp_eq_u32 s99, 11
	s_cbranch_scc0 .Lcf_skip_2_25
	s_add_u32 s100, s68, 0x162c7c40
	s_addc_u32 s101, s69, 0
	global_store_dword v21, v26, s[100:101]
.Lcf_skip_2_25:
	v_fma_f32 v26, v104, v26, v105
	s_cmp_eq_u32 s99, 12
	s_cbranch_scc0 .Lcf_skip_2_26
	s_add_u32 s100, s68, 0x162c8c40
	s_addc_u32 s101, s69, 0
	global_store_dword v21, v26, s[100:101]
.Lcf_skip_2_26:
	v_fma_f32 v26, v106, v26, v107
	s_cmp_eq_u32 s99, 13
	s_cbranch_scc0 .Lcf_skip_2_27
	s_add_u32 s100, s68, 0x162c9c40
	s_addc_u32 s101, s69, 0
	global_store_dword v21, v26, s[100:101]
.Lcf_skip_2_27:
	v_fma_f32 v26, v108, v26, v109
	s_cmp_eq_u32 s99, 14
	s_cbranch_scc0 .Lcf_skip_2_28
	s_add_u32 s100, s68, 0x162cac40
	s_addc_u32 s101, s69, 0
	global_store_dword v21, v26, s[100:101]
.Lcf_skip_2_28:
	v_fma_f32 v26, v110, v26, v111
	s_cmp_eq_u32 s99, 15
	s_cbranch_scc0 .Lcf_skip_2_29
	s_add_u32 s100, s68, 0x162cbc40
	s_addc_u32 s101, s69, 0
	global_store_dword v21, v26, s[100:101]
.Lcf_skip_2_29:
	v_fma_f32 v26, v112, v26, v113
	s_cmp_eq_u32 s99, 0
	s_cbranch_scc0 .Lcf_skip_2_30
	s_add_u32 s100, s68, 0x162ccc40
	s_addc_u32 s101, s69, 0
	global_store_dword v21, v26, s[100:101]
.Lcf_skip_2_30:
	v_fma_f32 v26, v114, v26, v115
	s_cmp_eq_u32 s99, 1
	s_cbranch_scc0 .Lcf_skip_2_31
	s_add_u32 s100, s68, 0x162cdc40
	s_addc_u32 s101, s69, 0
	global_store_dword v21, v26, s[100:101]
.Lcf_skip_2_31:
	v_fma_f32 v26, v116, v26, v117
	s_cmp_eq_u32 s99, 2
	s_cbranch_scc0 .Lcf_skip_2_32
	s_add_u32 s100, s68, 0x162cec40
	s_addc_u32 s101, s69, 0
	global_store_dword v21, v26, s[100:101]

.Lcf_var_3:
	s_add_u32 s100, s68, 0x1612ac40
	s_addc_u32 s101, s69, 0
	global_load_dwordx2 v[48:49], v20, s[100:101]
	s_add_u32 s100, s68, 0x1612cc40
	s_addc_u32 s101, s69, 0
	global_load_dwordx2 v[50:51], v20, s[100:101]
	s_add_u32 s100, s68, 0x1612ec40
	s_addc_u32 s101, s69, 0
	global_load_dwordx2 v[52:53], v20, s[100:101]
	s_add_u32 s100, s68, 0x16130c40
	s_addc_u32 s101, s69, 0
	global_load_dwordx2 v[54:55], v20, s[100:101]
	s_add_u32 s100, s68, 0x16132c40
	s_addc_u32 s101, s69, 0
	global_load_dwordx2 v[56:57], v20, s[100:101]
	s_add_u32 s100, s68, 0x16134c40
	s_addc_u32 s101, s69, 0
	global_load_dwordx2 v[58:59], v20, s[100:101]
	s_add_u32 s100, s68, 0x16136c40
	s_addc_u32 s101, s69, 0
	global_load_dwordx2 v[60:61], v20, s[100:101]
	s_add_u32 s100, s68, 0x16138c40
	s_addc_u32 s101, s69, 0
	global_load_dwordx2 v[62:63], v20, s[100:101]
	s_add_u32 s100, s68, 0x1613ac40
	s_addc_u32 s101, s69, 0
	global_load_dwordx2 v[64:65], v20, s[100:101]
	s_add_u32 s100, s68, 0x1613cc40
	s_addc_u32 s101, s69, 0
	global_load_dwordx2 v[66:67], v20, s[100:101]
	s_add_u32 s100, s68, 0x1613ec40
	s_addc_u32 s101, s69, 0
	global_load_dwordx2 v[68:69], v20, s[100:101]
	s_add_u32 s100, s68, 0x16140c40
	s_addc_u32 s101, s69, 0
	global_load_dwordx2 v[70:71], v20, s[100:101]
	s_add_u32 s100, s68, 0x16142c40
	s_addc_u32 s101, s69, 0
	global_load_dwordx2 v[78:79], v20, s[100:101]
	s_add_u32 s100, s68, 0x16144c40
	s_addc_u32 s101, s69, 0
	global_load_dwordx2 v[80:81], v20, s[100:101]
	s_add_u32 s100, s68, 0x16146c40
	s_addc_u32 s101, s69, 0
	global_load_dwordx2 v[82:83], v20, s[100:101]
	s_add_u32 s100, s68, 0x16148c40
	s_addc_u32 s101, s69, 0
	global_load_dwordx2 v[84:85], v20, s[100:101]
	s_add_u32 s100, s68, 0x1614ac40
	s_addc_u32 s101, s69, 0
	global_load_dwordx2 v[86:87], v20, s[100:101]
	s_add_u32 s100, s68, 0x1614cc40
	s_addc_u32 s101, s69, 0
	global_load_dwordx2 v[88:89], v20, s[100:101]
	s_add_u32 s100, s68, 0x1614ec40
	s_addc_u32 s101, s69, 0
	global_load_dwordx2 v[90:91], v20, s[100:101]
	s_add_u32 s100, s68, 0x16150c40
	s_addc_u32 s101, s69, 0
	global_load_dwordx2 v[92:93], v20, s[100:101]
	s_add_u32 s100, s68, 0x16152c40
	s_addc_u32 s101, s69, 0
	global_load_dwordx2 v[94:95], v20, s[100:101]
	s_add_u32 s100, s68, 0x16154c40
	s_addc_u32 s101, s69, 0
	global_load_dwordx2 v[96:97], v20, s[100:101]
	s_add_u32 s100, s68, 0x16156c40
	s_addc_u32 s101, s69, 0
	global_load_dwordx2 v[98:99], v20, s[100:101]
	s_add_u32 s100, s68, 0x16158c40
	s_addc_u32 s101, s69, 0
	global_load_dwordx2 v[100:101], v20, s[100:101]
	s_add_u32 s100, s68, 0x1615ac40
	s_addc_u32 s101, s69, 0
	global_load_dwordx2 v[102:103], v20, s[100:101]
	s_add_u32 s100, s68, 0x1615cc40
	s_addc_u32 s101, s69, 0
	global_load_dwordx2 v[104:105], v20, s[100:101]
	s_add_u32 s100, s68, 0x1615ec40
	s_addc_u32 s101, s69, 0
	global_load_dwordx2 v[106:107], v20, s[100:101]
	s_add_u32 s100, s68, 0x16160c40
	s_addc_u32 s101, s69, 0
	global_load_dwordx2 v[108:109], v20, s[100:101]
	s_add_u32 s100, s68, 0x16162c40
	s_addc_u32 s101, s69, 0
	global_load_dwordx2 v[110:111], v20, s[100:101]
	s_add_u32 s100, s68, 0x16164c40
	s_addc_u32 s101, s69, 0
	global_load_dwordx2 v[112:113], v20, s[100:101]
	s_add_u32 s100, s68, 0x16166c40
	s_addc_u32 s101, s69, 0
	global_load_dwordx2 v[114:115], v20, s[100:101]
	v_mov_b32_e32 v24, 1.0
	v_mov_b32_e32 v25, 0
	s_waitcnt vmcnt(30)
	v_fma_f32 v25, v48, v25, v49
	v_mul_f32_e32 v24, v24, v48
	s_waitcnt vmcnt(29)
	v_fma_f32 v25, v50, v25, v51
	v_mul_f32_e32 v24, v24, v50
	s_waitcnt vmcnt(28)
	v_fma_f32 v25, v52, v25, v53
	v_mul_f32_e32 v24, v24, v52
	s_waitcnt vmcnt(27)
	v_fma_f32 v25, v54, v25, v55
	v_mul_f32_e32 v24, v24, v54
	s_waitcnt vmcnt(26)
	v_fma_f32 v25, v56, v25, v57
	v_mul_f32_e32 v24, v24, v56
	s_waitcnt vmcnt(25)
	v_fma_f32 v25, v58, v25, v59
	v_mul_f32_e32 v24, v24, v58
	s_waitcnt vmcnt(24)
	v_fma_f32 v25, v60, v25, v61
	v_mul_f32_e32 v24, v24, v60
	s_waitcnt vmcnt(23)
	v_fma_f32 v25, v62, v25, v63
	v_mul_f32_e32 v24, v24, v62
	s_waitcnt vmcnt(22)
	v_fma_f32 v25, v64, v25, v65
	v_mul_f32_e32 v24, v24, v64
	s_waitcnt vmcnt(21)
	v_fma_f32 v25, v66, v25, v67
	v_mul_f32_e32 v24, v24, v66
	s_waitcnt vmcnt(20)
	v_fma_f32 v25, v68, v25, v69
	v_mul_f32_e32 v24, v24, v68
	s_waitcnt vmcnt(19)
	v_fma_f32 v25, v70, v25, v71
	v_mul_f32_e32 v24, v24, v70
	s_waitcnt vmcnt(18)
	v_fma_f32 v25, v78, v25, v79
	v_mul_f32_e32 v24, v24, v78
	s_waitcnt vmcnt(17)
	v_fma_f32 v25, v80, v25, v81
	v_mul_f32_e32 v24, v24, v80
	s_waitcnt vmcnt(16)
	v_fma_f32 v25, v82, v25, v83
	v_mul_f32_e32 v24, v24, v82
	s_waitcnt vmcnt(15)
	v_fma_f32 v25, v84, v25, v85
	v_mul_f32_e32 v24, v24, v84
	s_waitcnt vmcnt(14)
	v_fma_f32 v25, v86, v25, v87
	v_mul_f32_e32 v24, v24, v86
	s_waitcnt vmcnt(13)
	v_fma_f32 v25, v88, v25, v89
	v_mul_f32_e32 v24, v24, v88
	s_waitcnt vmcnt(12)
	v_fma_f32 v25, v90, v25, v91
	v_mul_f32_e32 v24, v24, v90
	s_waitcnt vmcnt(11)
	v_fma_f32 v25, v92, v25, v93
	v_mul_f32_e32 v24, v24, v92
	s_waitcnt vmcnt(10)
	v_fma_f32 v25, v94, v25, v95
	v_mul_f32_e32 v24, v24, v94
	s_waitcnt vmcnt(9)
	v_fma_f32 v25, v96, v25, v97
	v_mul_f32_e32 v24, v24, v96
	s_waitcnt vmcnt(8)
	v_fma_f32 v25, v98, v25, v99
	v_mul_f32_e32 v24, v24, v98
	s_waitcnt vmcnt(7)
	v_fma_f32 v25, v100, v25, v101
	v_mul_f32_e32 v24, v24, v100
	s_waitcnt vmcnt(6)
	v_fma_f32 v25, v102, v25, v103
	v_mul_f32_e32 v24, v24, v102
	s_waitcnt vmcnt(5)
	v_fma_f32 v25, v104, v25, v105
	v_mul_f32_e32 v24, v24, v104
	s_waitcnt vmcnt(4)
	v_fma_f32 v25, v106, v25, v107
	v_mul_f32_e32 v24, v24, v106
	s_waitcnt vmcnt(3)
	v_fma_f32 v25, v108, v25, v109
	v_mul_f32_e32 v24, v24, v108
	s_waitcnt vmcnt(2)
	v_fma_f32 v25, v110, v25, v111
	v_mul_f32_e32 v24, v24, v110
	s_waitcnt vmcnt(1)
	v_fma_f32 v25, v112, v25, v113
	v_mul_f32_e32 v24, v24, v112
	s_waitcnt vmcnt(0)
	v_fma_f32 v25, v114, v25, v115
	v_mul_f32_e32 v24, v24, v114
	ds_write_b64 v22, v[24:25] offset:1536
	s_waitcnt lgkmcnt(0)
	s_barrier
	v_mov_b32_e32 v26, 0
	ds_read_b64 v[28:29], v22 offset:0
	s_waitcnt lgkmcnt(0)
	v_fma_f32 v26, v28, v26, v29
	ds_read_b64 v[28:29], v22 offset:512
	s_waitcnt lgkmcnt(0)
	v_fma_f32 v26, v28, v26, v29
	ds_read_b64 v[28:29], v22 offset:1024
	s_waitcnt lgkmcnt(0)
	v_fma_f32 v26, v28, v26, v29
	s_cmp_eq_u32 s99, 3
	s_cbranch_scc0 .Lcf_skip_3_0
	s_add_u32 s100, s68, 0x162cfc40
	s_addc_u32 s101, s69, 0
	global_store_dword v21, v26, s[100:101]
.Lcf_skip_3_0:
	v_fma_f32 v26, v48, v26, v49
	s_cmp_eq_u32 s99, 4
	s_cbranch_scc0 .Lcf_skip_3_1
	s_add_u32 s100, s68, 0x162d0c40
	s_addc_u32 s101, s69, 0
	global_store_dword v21, v26, s[100:101]
.Lcf_skip_3_1:
	v_fma_f32 v26, v50, v26, v51
	s_cmp_eq_u32 s99, 5
	s_cbranch_scc0 .Lcf_skip_3_2
	s_add_u32 s100, s68, 0x162d1c40
	s_addc_u32 s101, s69, 0
	global_store_dword v21, v26, s[100:101]
.Lcf_skip_3_2:
	v_fma_f32 v26, v52, v26, v53
	s_cmp_eq_u32 s99, 6
	s_cbranch_scc0 .Lcf_skip_3_3
	s_add_u32 s100, s68, 0x162d2c40
	s_addc_u32 s101, s69, 0
	global_store_dword v21, v26, s[100:101]
.Lcf_skip_3_3:
	v_fma_f32 v26, v54, v26, v55
	s_cmp_eq_u32 s99, 7
	s_cbranch_scc0 .Lcf_skip_3_4
	s_add_u32 s100, s68, 0x162d3c40
	s_addc_u32 s101, s69, 0
	global_store_dword v21, v26, s[100:101]
.Lcf_skip_3_4:
	v_fma_f32 v26, v56, v26, v57
	s_cmp_eq_u32 s99, 8
	s_cbranch_scc0 .Lcf_skip_3_5
	s_add_u32 s100, s68, 0x162d4c40
	s_addc_u32 s101, s69, 0
	global_store_dword v21, v26, s[100:101]
.Lcf_skip_3_5:
	v_fma_f32 v26, v58, v26, v59
	s_cmp_eq_u32 s99, 9
	s_cbranch_scc0 .Lcf_skip_3_6
	s_add_u32 s100, s68, 0x162d5c40
	s_addc_u32 s101, s69, 0
	global_store_dword v21, v26, s[100:101]
.Lcf_skip_3_6:
	v_fma_f32 v26, v60, v26, v61
	s_cmp_eq_u32 s99, 10
	s_cbranch_scc0 .Lcf_skip_3_7
	s_add_u32 s100, s68, 0x162d6c40
	s_addc_u32 s101, s69, 0
	global_store_dword v21, v26, s[100:101]
.Lcf_skip_3_7:
	v_fma_f32 v26, v62, v26, v63
	s_cmp_eq_u32 s99, 11
	s_cbranch_scc0 .Lcf_skip_3_8
	s_add_u32 s100, s68, 0x162d7c40
	s_addc_u32 s101, s69, 0
	global_store_dword v21, v26, s[100:101]
.Lcf_skip_3_8:
	v_fma_f32 v26, v64, v26, v65
	s_cmp_eq_u32 s99, 12
	s_cbranch_scc0 .Lcf_skip_3_9
	s_add_u32 s100, s68, 0x162d8c40
	s_addc_u32 s101, s69, 0
	global_store_dword v21, v26, s[100:101]
.Lcf_skip_3_9:
	v_fma_f32 v26, v66, v26, v67
	s_cmp_eq_u32 s99, 13
	s_cbranch_scc0 .Lcf_skip_3_10
	s_add_u32 s100, s68, 0x162d9c40
	s_addc_u32 s101, s69, 0
	global_store_dword v21, v26, s[100:101]
.Lcf_skip_3_10:
	v_fma_f32 v26, v68, v26, v69
	s_cmp_eq_u32 s99, 14
	s_cbranch_scc0 .Lcf_skip_3_11
	s_add_u32 s100, s68, 0x162dac40
	s_addc_u32 s101, s69, 0
	global_store_dword v21, v26, s[100:101]
.Lcf_skip_3_11:
	v_fma_f32 v26, v70, v26, v71
	s_cmp_eq_u32 s99, 15
	s_cbranch_scc0 .Lcf_skip_3_12
	s_add_u32 s100, s68, 0x162dbc40
	s_addc_u32 s101, s69, 0
	global_store_dword v21, v26, s[100:101]
.Lcf_skip_3_12:
	v_fma_f32 v26, v78, v26, v79
	s_cmp_eq_u32 s99, 0
	s_cbranch_scc0 .Lcf_skip_3_13
	s_add_u32 s100, s68, 0x162dcc40
	s_addc_u32 s101, s69, 0
	global_store_dword v21, v26, s[100:101]
.Lcf_skip_3_13:
	v_fma_f32 v26, v80, v26, v81
	s_cmp_eq_u32 s99, 1
	s_cbranch_scc0 .Lcf_skip_3_14
	s_add_u32 s100, s68, 0x162ddc40
	s_addc_u32 s101, s69, 0
	global_store_dword v21, v26, s[100:101]
.Lcf_skip_3_14:
	v_fma_f32 v26, v82, v26, v83
	s_cmp_eq_u32 s99, 2
	s_cbranch_scc0 .Lcf_skip_3_15
	s_add_u32 s100, s68, 0x162dec40
	s_addc_u32 s101, s69, 0
	global_store_dword v21, v26, s[100:101]
.Lcf_skip_3_15:
	v_fma_f32 v26, v84, v26, v85
	s_cmp_eq_u32 s99, 3
	s_cbranch_scc0 .Lcf_skip_3_16
	s_add_u32 s100, s68, 0x162dfc40
	s_addc_u32 s101, s69, 0
	global_store_dword v21, v26, s[100:101]
.Lcf_skip_3_16:
	v_fma_f32 v26, v86, v26, v87
	s_cmp_eq_u32 s99, 4
	s_cbranch_scc0 .Lcf_skip_3_17
	s_add_u32 s100, s68, 0x162e0c40
	s_addc_u32 s101, s69, 0
	global_store_dword v21, v26, s[100:101]
.Lcf_skip_3_17:
	v_fma_f32 v26, v88, v26, v89
	s_cmp_eq_u32 s99, 5
	s_cbranch_scc0 .Lcf_skip_3_18
	s_add_u32 s100, s68, 0x162e1c40
	s_addc_u32 s101, s69, 0
	global_store_dword v21, v26, s[100:101]
.Lcf_skip_3_18:
	v_fma_f32 v26, v90, v26, v91
	s_cmp_eq_u32 s99, 6
	s_cbranch_scc0 .Lcf_skip_3_19
	s_add_u32 s100, s68, 0x162e2c40
	s_addc_u32 s101, s69, 0
	global_store_dword v21, v26, s[100:101]
.Lcf_skip_3_19:
	v_fma_f32 v26, v92, v26, v93
	s_cmp_eq_u32 s99, 7
	s_cbranch_scc0 .Lcf_skip_3_20
	s_add_u32 s100, s68, 0x162e3c40
	s_addc_u32 s101, s69, 0
	global_store_dword v21, v26, s[100:101]
.Lcf_skip_3_20:
	v_fma_f32 v26, v94, v26, v95
	s_cmp_eq_u32 s99, 8
	s_cbranch_scc0 .Lcf_skip_3_21
	s_add_u32 s100, s68, 0x162e4c40
	s_addc_u32 s101, s69, 0
	global_store_dword v21, v26, s[100:101]
.Lcf_skip_3_21:
	v_fma_f32 v26, v96, v26, v97
	s_cmp_eq_u32 s99, 9
	s_cbranch_scc0 .Lcf_skip_3_22
	s_add_u32 s100, s68, 0x162e5c40
	s_addc_u32 s101, s69, 0
	global_store_dword v21, v26, s[100:101]
.Lcf_skip_3_22:
	v_fma_f32 v26, v98, v26, v99
	s_cmp_eq_u32 s99, 10
	s_cbranch_scc0 .Lcf_skip_3_23
	s_add_u32 s100, s68, 0x162e6c40
	s_addc_u32 s101, s69, 0
	global_store_dword v21, v26, s[100:101]
.Lcf_skip_3_23:
	v_fma_f32 v26, v100, v26, v101
	s_cmp_eq_u32 s99, 11
	s_cbranch_scc0 .Lcf_skip_3_24
	s_add_u32 s100, s68, 0x162e7c40
	s_addc_u32 s101, s69, 0
	global_store_dword v21, v26, s[100:101]
.Lcf_skip_3_24:
	v_fma_f32 v26, v102, v26, v103
	s_cmp_eq_u32 s99, 12
	s_cbranch_scc0 .Lcf_skip_3_25
	s_add_u32 s100, s68, 0x162e8c40
	s_addc_u32 s101, s69, 0
	global_store_dword v21, v26, s[100:101]
.Lcf_skip_3_25:
	v_fma_f32 v26, v104, v26, v105
	s_cmp_eq_u32 s99, 13
	s_cbranch_scc0 .Lcf_skip_3_26
	s_add_u32 s100, s68, 0x162e9c40
	s_addc_u32 s101, s69, 0
	global_store_dword v21, v26, s[100:101]
.Lcf_skip_3_26:
	v_fma_f32 v26, v106, v26, v107
	s_cmp_eq_u32 s99, 14
	s_cbranch_scc0 .Lcf_skip_3_27
	s_add_u32 s100, s68, 0x162eac40
	s_addc_u32 s101, s69, 0
	global_store_dword v21, v26, s[100:101]
.Lcf_skip_3_27:
	v_fma_f32 v26, v108, v26, v109
	s_cmp_eq_u32 s99, 15
	s_cbranch_scc0 .Lcf_skip_3_28
	s_add_u32 s100, s68, 0x162ebc40
	s_addc_u32 s101, s69, 0
	global_store_dword v21, v26, s[100:101]
.Lcf_skip_3_28:
	v_fma_f32 v26, v110, v26, v111
	s_cmp_eq_u32 s99, 0
	s_cbranch_scc0 .Lcf_skip_3_29
	s_add_u32 s100, s68, 0x162ecc40
	s_addc_u32 s101, s69, 0
	global_store_dword v21, v26, s[100:101]
.Lcf_skip_3_29:
	v_fma_f32 v26, v112, v26, v113
	s_cmp_eq_u32 s99, 1
	s_cbranch_scc0 .Lcf_skip_3_30
	s_add_u32 s100, s68, 0x162edc40
	s_addc_u32 s101, s69, 0
	global_store_dword v21, v26, s[100:101]
.Lcf_skip_3_30:
	v_fma_f32 v26, v114, v26, v115
	s_branch .Lcf_join
.Lcf_var_4:
	s_add_u32 s100, s68, 0x1616ac40
	s_addc_u32 s101, s69, 0
	global_load_dwordx2 v[48:49], v20, s[100:101]
	s_add_u32 s100, s68, 0x16168c40
	s_addc_u32 s101, s69, 0
	global_load_dwordx2 v[50:51], v20, s[100:101]
	s_add_u32 s100, s68, 0x1626ac40
	s_addc_u32 s101, s69, 0
	global_load_dwordx2 v[52:53], v20, s[100:101]
	s_add_u32 s100, s68, 0x16268c40
	s_addc_u32 s101, s69, 0
	global_load_dwordx2 v[54:55], v20, s[100:101]
	s_add_u32 s100, s68, 0x16266c40
	s_addc_u32 s101, s69, 0
	global_load_dwordx2 v[56:57], v20, s[100:101]
	s_add_u32 s100, s68, 0x16264c40
	s_addc_u32 s101, s69, 0
	global_load_dwordx2 v[58:59], v20, s[100:101]
	s_add_u32 s100, s68, 0x16262c40
	s_addc_u32 s101, s69, 0
	global_load_dwordx2 v[60:61], v20, s[100:101]
	s_add_u32 s100, s68, 0x16260c40
	s_addc_u32 s101, s69, 0
	global_load_dwordx2 v[62:63], v20, s[100:101]
	s_add_u32 s100, s68, 0x1625ec40
	s_addc_u32 s101, s69, 0
	global_load_dwordx2 v[64:65], v20, s[100:101]
	s_add_u32 s100, s68, 0x1625cc40
	s_addc_u32 s101, s69, 0
	global_load_dwordx2 v[66:67], v20, s[100:101]
	s_add_u32 s100, s68, 0x1625ac40
	s_addc_u32 s101, s69, 0
	global_load_dwordx2 v[68:69], v20, s[100:101]
	s_add_u32 s100, s68, 0x16258c40
	s_addc_u32 s101, s69, 0
	global_load_dwordx2 v[70:71], v20, s[100:101]
	s_add_u32 s100, s68, 0x16256c40
	s_addc_u32 s101, s69, 0
	global_load_dwordx2 v[78:79], v20, s[100:101]
	s_add_u32 s100, s68, 0x16254c40
	s_addc_u32 s101, s69, 0
	global_load_dwordx2 v[80:81], v20, s[100:101]
	s_add_u32 s100, s68, 0x16252c40
	s_addc_u32 s101, s69, 0
	global_load_dwordx2 v[82:83], v20, s[100:101]
	s_add_u32 s100, s68, 0x16250c40
	s_addc_u32 s101, s69, 0
	global_load_dwordx2 v[84:85], v20, s[100:101]
	s_add_u32 s100, s68, 0x1624ec40
	s_addc_u32 s101, s69, 0
	global_load_dwordx2 v[86:87], v20, s[100:101]
	s_add_u32 s100, s68, 0x1624cc40
	s_addc_u32 s101, s69, 0
	global_load_dwordx2 v[88:89], v20, s[100:101]
	s_add_u32 s100, s68, 0x1624ac40
	s_addc_u32 s101, s69, 0
	global_load_dwordx2 v[90:91], v20, s[100:101]
	s_add_u32 s100, s68, 0x16248c40
	s_addc_u32 s101, s69, 0
	global_load_dwordx2 v[92:93], v20, s[100:101]
	s_add_u32 s100, s68, 0x16246c40
	s_addc_u32 s101, s69, 0
	global_load_dwordx2 v[94:95], v20, s[100:101]
	s_add_u32 s100, s68, 0x16244c40
	s_addc_u32 s101, s69, 0
	global_load_dwordx2 v[96:97], v20, s[100:101]
	s_add_u32 s100, s68, 0x16242c40
	s_addc_u32 s101, s69, 0
	global_load_dwordx2 v[98:99], v20, s[100:101]
	s_add_u32 s100, s68, 0x16240c40
	s_addc_u32 s101, s69, 0
	global_load_dwordx2 v[100:101], v20, s[100:101]
	s_add_u32 s100, s68, 0x1623ec40
	s_addc_u32 s101, s69, 0
	global_load_dwordx2 v[102:103], v20, s[100:101]
	s_add_u32 s100, s68, 0x1623cc40
	s_addc_u32 s101, s69, 0
	global_load_dwordx2 v[104:105], v20, s[100:101]
	s_add_u32 s100, s68, 0x1623ac40
	s_addc_u32 s101, s69, 0
	global_load_dwordx2 v[106:107], v20, s[100:101]
	s_add_u32 s100, s68, 0x16238c40
	s_addc_u32 s101, s69, 0
	global_load_dwordx2 v[108:109], v20, s[100:101]
	s_add_u32 s100, s68, 0x16236c40
	s_addc_u32 s101, s69, 0
	global_load_dwordx2 v[110:111], v20, s[100:101]
	s_add_u32 s100, s68, 0x16234c40
	s_addc_u32 s101, s69, 0
	global_load_dwordx2 v[112:113], v20, s[100:101]
	s_add_u32 s100, s68, 0x16232c40
	s_addc_u32 s101, s69, 0
	global_load_dwordx2 v[114:115], v20, s[100:101]
	s_add_u32 s100, s68, 0x16230c40
	s_addc_u32 s101, s69, 0
	global_load_dwordx2 v[116:117], v20, s[100:101]
	s_add_u32 s100, s68, 0x1622ec40
	s_addc_u32 s101, s69, 0
	global_load_dwordx2 v[118:119], v20, s[100:101]
	v_mov_b32_e32 v24, 1.0
	v_mov_b32_e32 v25, 0
	s_waitcnt vmcnt(32)
	v_fma_f32 v25, v48, v25, v49
	v_mul_f32_e32 v24, v24, v48
	s_waitcnt vmcnt(31)
	v_fma_f32 v25, v50, v25, v51
	v_mul_f32_e32 v24, v24, v50
	s_waitcnt vmcnt(30)
	v_fma_f32 v25, v52, v25, v53
	v_mul_f32_e32 v24, v24, v52
	s_waitcnt vmcnt(29)
	v_fma_f32 v25, v54, v25, v55
	v_mul_f32_e32 v24, v24, v54
	s_waitcnt vmcnt(28)
	v_fma_f32 v25, v56, v25, v57
	v_mul_f32_e32 v24, v24, v56
	s_waitcnt vmcnt(27)
	v_fma_f32 v25, v58, v25, v59
	v_mul_f32_e32 v24, v24, v58
	s_waitcnt vmcnt(26)
	v_fma_f32 v25, v60, v25, v61
	v_mul_f32_e32 v24, v24, v60
	s_waitcnt vmcnt(25)
	v_fma_f32 v25, v62, v25, v63
	v_mul_f32_e32 v24, v24, v62
	s_waitcnt vmcnt(24)
	v_fma_f32 v25, v64, v25, v65
	v_mul_f32_e32 v24, v24, v64
	s_waitcnt vmcnt(23)
	v_fma_f32 v25, v66, v25, v67
	v_mul_f32_e32 v24, v24, v66
	s_waitcnt vmcnt(22)
	v_fma_f32 v25, v68, v25, v69
	v_mul_f32_e32 v24, v24, v68
	s_waitcnt vmcnt(21)
	v_fma_f32 v25, v70, v25, v71
	v_mul_f32_e32 v24, v24, v70
	s_waitcnt vmcnt(20)
	v_fma_f32 v25, v78, v25, v79
	v_mul_f32_e32 v24, v24, v78
	s_waitcnt vmcnt(19)
	v_fma_f32 v25, v80, v25, v81
	v_mul_f32_e32 v24, v24, v80
	s_waitcnt vmcnt(18)
	v_fma_f32 v25, v82, v25, v83
	v_mul_f32_e32 v24, v24, v82
	s_waitcnt vmcnt(17)
	v_fma_f32 v25, v84, v25, v85
	v_mul_f32_e32 v24, v24, v84
	s_waitcnt vmcnt(16)
	v_fma_f32 v25, v86, v25, v87
	v_mul_f32_e32 v24, v24, v86
	s_waitcnt vmcnt(15)
	v_fma_f32 v25, v88, v25, v89
	v_mul_f32_e32 v24, v24, v88
	s_waitcnt vmcnt(14)
	v_fma_f32 v25, v90, v25, v91
	v_mul_f32_e32 v24, v24, v90
	s_waitcnt vmcnt(13)
	v_fma_f32 v25, v92, v25, v93
	v_mul_f32_e32 v24, v24, v92
	s_waitcnt vmcnt(12)
	v_fma_f32 v25, v94, v25, v95
	v_mul_f32_e32 v24, v24, v94
	s_waitcnt vmcnt(11)
	v_fma_f32 v25, v96, v25, v97
	v_mul_f32_e32 v24, v24, v96
	s_waitcnt vmcnt(10)
	v_fma_f32 v25, v98, v25, v99
	v_mul_f32_e32 v24, v24, v98
	s_waitcnt vmcnt(9)
	v_fma_f32 v25, v100, v25, v101
	v_mul_f32_e32 v24, v24, v100
	s_waitcnt vmcnt(8)
	v_fma_f32 v25, v102, v25, v103
	v_mul_f32_e32 v24, v24, v102
	s_waitcnt vmcnt(7)
	v_fma_f32 v25, v104, v25, v105
	v_mul_f32_e32 v24, v24, v104
	s_waitcnt vmcnt(6)
	v_fma_f32 v25, v106, v25, v107
	v_mul_f32_e32 v24, v24, v106
	s_waitcnt vmcnt(5)
	v_fma_f32 v25, v108, v25, v109
	v_mul_f32_e32 v24, v24, v108
	s_waitcnt vmcnt(4)
	v_fma_f32 v25, v110, v25, v111
	v_mul_f32_e32 v24, v24, v110
	s_waitcnt vmcnt(3)
	v_fma_f32 v25, v112, v25, v113
	v_mul_f32_e32 v24, v24, v112
	s_waitcnt vmcnt(2)
	v_fma_f32 v25, v114, v25, v115
	v_mul_f32_e32 v24, v24, v114
	s_waitcnt vmcnt(1)
	v_fma_f32 v25, v116, v25, v117
	v_mul_f32_e32 v24, v24, v116
	s_waitcnt vmcnt(0)
	v_fma_f32 v25, v118, v25, v119
	v_mul_f32_e32 v24, v24, v118
	ds_write_b64 v22, v[24:25] offset:2048
	s_waitcnt lgkmcnt(0)
	s_barrier
	v_mov_b32_e32 v26, 0
	s_cmp_eq_u32 s99, 1
	s_cbranch_scc0 .Lcf_skip_4_0
	s_add_u32 s100, s68, 0x162efc40
	s_addc_u32 s101, s69, 0
	global_store_dword v21, v26, s[100:101]
.Lcf_skip_4_0:
	v_fma_f32 v26, v48, v26, v49
	s_cmp_eq_u32 s99, 0
	s_cbranch_scc0 .Lcf_skip_4_1
	s_add_u32 s100, s68, 0x162eec40
	s_addc_u32 s101, s69, 0
	global_store_dword v21, v26, s[100:101]
.Lcf_skip_4_1:
	v_fma_f32 v26, v50, v26, v51
	s_cmp_eq_u32 s99, 1
	s_cbranch_scc0 .Lcf_skip_4_2
	s_add_u32 s100, s68, 0x1636fc40
	s_addc_u32 s101, s69, 0
	global_store_dword v21, v26, s[100:101]
.Lcf_skip_4_2:
	v_fma_f32 v26, v52, v26, v53
	s_cmp_eq_u32 s99, 0
	s_cbranch_scc0 .Lcf_skip_4_3
	s_add_u32 s100, s68, 0x1636ec40
	s_addc_u32 s101, s69, 0
	global_store_dword v21, v26, s[100:101]
.Lcf_skip_4_3:
	v_fma_f32 v26, v54, v26, v55
	s_cmp_eq_u32 s99, 15
	s_cbranch_scc0 .Lcf_skip_4_4
	s_add_u32 s100, s68, 0x1636dc40
	s_addc_u32 s101, s69, 0
	global_store_dword v21, v26, s[100:101]
.Lcf_skip_4_4:
	v_fma_f32 v26, v56, v26, v57
	s_cmp_eq_u32 s99, 14
	s_cbranch_scc0 .Lcf_skip_4_5
	s_add_u32 s100, s68, 0x1636cc40
	s_addc_u32 s101, s69, 0
	global_store_dword v21, v26, s[100:101]
.Lcf_skip_4_5:
	v_fma_f32 v26, v58, v26, v59
	s_cmp_eq_u32 s99, 13
	s_cbranch_scc0 .Lcf_skip_4_6
	s_add_u32 s100, s68, 0x1636bc40
	s_addc_u32 s101, s69, 0
	global_store_dword v21, v26, s[100:101]
.Lcf_skip_4_6:
	v_fma_f32 v26, v60, v26, v61
	s_cmp_eq_u32 s99, 12
	s_cbranch_scc0 .Lcf_skip_4_7
	s_add_u32 s100, s68, 0x1636ac40
	s_addc_u32 s101, s69, 0
	global_store_dword v21, v26, s[100:101]
.Lcf_skip_4_7:
	v_fma_f32 v26, v62, v26, v63
	s_cmp_eq_u32 s99, 11
	s_cbranch_scc0 .Lcf_skip_4_8
	s_add_u32 s100, s68, 0x16369c40
	s_addc_u32 s101, s69, 0
	global_store_dword v21, v26, s[100:101]
.Lcf_skip_4_8:
	v_fma_f32 v26, v64, v26, v65
	s_cmp_eq_u32 s99, 10
	s_cbranch_scc0 .Lcf_skip_4_9
	s_add_u32 s100, s68, 0x16368c40
	s_addc_u32 s101, s69, 0
	global_store_dword v21, v26, s[100:101]
.Lcf_skip_4_9:
	v_fma_f32 v26, v66, v26, v67
	s_cmp_eq_u32 s99, 9
	s_cbranch_scc0 .Lcf_skip_4_10
	s_add_u32 s100, s68, 0x16367c40
	s_addc_u32 s101, s69, 0
	global_store_dword v21, v26, s[100:101]
.Lcf_skip_4_10:
	v_fma_f32 v26, v68, v26, v69
	s_cmp_eq_u32 s99, 8
	s_cbranch_scc0 .Lcf_skip_4_11
	s_add_u32 s100, s68, 0x16366c40
	s_addc_u32 s101, s69, 0
	global_store_dword v21, v26, s[100:101]
.Lcf_skip_4_11:
	v_fma_f32 v26, v70, v26, v71
	s_cmp_eq_u32 s99, 7
	s_cbranch_scc0 .Lcf_skip_4_12
	s_add_u32 s100, s68, 0x16365c40
	s_addc_u32 s101, s69, 0
	global_store_dword v21, v26, s[100:101]
.Lcf_skip_4_12:
	v_fma_f32 v26, v78, v26, v79
	s_cmp_eq_u32 s99, 6
	s_cbranch_scc0 .Lcf_skip_4_13
	s_add_u32 s100, s68, 0x16364c40
	s_addc_u32 s101, s69, 0
	global_store_dword v21, v26, s[100:101]
.Lcf_skip_4_13:
	v_fma_f32 v26, v80, v26, v81
	s_cmp_eq_u32 s99, 5
	s_cbranch_scc0 .Lcf_skip_4_14
	s_add_u32 s100, s68, 0x16363c40
	s_addc_u32 s101, s69, 0
	global_store_dword v21, v26, s[100:101]
.Lcf_skip_4_14:
	v_fma_f32 v26, v82, v26, v83
	s_cmp_eq_u32 s99, 4
	s_cbranch_scc0 .Lcf_skip_4_15
	s_add_u32 s100, s68, 0x16362c40
	s_addc_u32 s101, s69, 0
	global_store_dword v21, v26, s[100:101]
.Lcf_skip_4_15:
	v_fma_f32 v26, v84, v26, v85
	s_cmp_eq_u32 s99, 3
	s_cbranch_scc0 .Lcf_skip_4_16
	s_add_u32 s100, s68, 0x16361c40
	s_addc_u32 s101, s69, 0
	global_store_dword v21, v26, s[100:101]
.Lcf_skip_4_16:
	v_fma_f32 v26, v86, v26, v87
	s_cmp_eq_u32 s99, 2
	s_cbranch_scc0 .Lcf_skip_4_17
	s_add_u32 s100, s68, 0x16360c40
	s_addc_u32 s101, s69, 0
	global_store_dword v21, v26, s[100:101]
.Lcf_skip_4_17:
	v_fma_f32 v26, v88, v26, v89
	s_cmp_eq_u32 s99, 1
	s_cbranch_scc0 .Lcf_skip_4_18
	s_add_u32 s100, s68, 0x1635fc40
	s_addc_u32 s101, s69, 0
	global_store_dword v21, v26, s[100:101]
.Lcf_skip_4_18:
	v_fma_f32 v26, v90, v26, v91
	s_cmp_eq_u32 s99, 0
	s_cbranch_scc0 .Lcf_skip_4_19
	s_add_u32 s100, s68, 0x1635ec40
	s_addc_u32 s101, s69, 0
	global_store_dword v21, v26, s[100:101]
.Lcf_skip_4_19:
	v_fma_f32 v26, v92, v26, v93
	s_cmp_eq_u32 s99, 15
	s_cbranch_scc0 .Lcf_skip_4_20
	s_add_u32 s100, s68, 0x1635dc40
	s_addc_u32 s101, s69, 0
	global_store_dword v21, v26, s[100:101]
.Lcf_skip_4_20:
	v_fma_f32 v26, v94, v26, v95
	s_cmp_eq_u32 s99, 14
	s_cbranch_scc0 .Lcf_skip_4_21
	s_add_u32 s100, s68, 0x1635cc40
	s_addc_u32 s101, s69, 0
	global_store_dword v21, v26, s[100:101]
.Lcf_skip_4_21:
	v_fma_f32 v26, v96, v26, v97
	s_cmp_eq_u32 s99, 13
	s_cbranch_scc0 .Lcf_skip_4_22
	s_add_u32 s100, s68, 0x1635bc40
	s_addc_u32 s101, s69, 0
	global_store_dword v21, v26, s[100:101]
.Lcf_skip_4_22:
	v_fma_f32 v26, v98, v26, v99
	s_cmp_eq_u32 s99, 12
	s_cbranch_scc0 .Lcf_skip_4_23
	s_add_u32 s100, s68, 0x1635ac40
	s_addc_u32 s101, s69, 0
	global_store_dword v21, v26, s[100:101]
.Lcf_skip_4_23:
	v_fma_f32 v26, v100, v26, v101
	s_cmp_eq_u32 s99, 11
	s_cbranch_scc0 .Lcf_skip_4_24
	s_add_u32 s100, s68, 0x16359c40
	s_addc_u32 s101, s69, 0
	global_store_dword v21, v26, s[100:101]
.Lcf_skip_4_24:
	v_fma_f32 v26, v102, v26, v103
	s_cmp_eq_u32 s99, 10
	s_cbranch_scc0 .Lcf_skip_4_25
	s_add_u32 s100, s68, 0x16358c40
	s_addc_u32 s101, s69, 0
	global_store_dword v21, v26, s[100:101]
.Lcf_skip_4_25:
	v_fma_f32 v26, v104, v26, v105
	s_cmp_eq_u32 s99, 9
	s_cbranch_scc0 .Lcf_skip_4_26
	s_add_u32 s100, s68, 0x16357c40
	s_addc_u32 s101, s69, 0
	global_store_dword v21, v26, s[100:101]
.Lcf_skip_4_26:
	v_fma_f32 v26, v106, v26, v107
	s_cmp_eq_u32 s99, 8
	s_cbranch_scc0 .Lcf_skip_4_27
	s_add_u32 s100, s68, 0x16356c40
	s_addc_u32 s101, s69, 0
	global_store_dword v21, v26, s[100:101]
.Lcf_skip_4_27:
	v_fma_f32 v26, v108, v26, v109
	s_cmp_eq_u32 s99, 7
	s_cbranch_scc0 .Lcf_skip_4_28
	s_add_u32 s100, s68, 0x16355c40
	s_addc_u32 s101, s69, 0
	global_store_dword v21, v26, s[100:101]
.Lcf_skip_4_28:
	v_fma_f32 v26, v110, v26, v111
	s_cmp_eq_u32 s99, 6
	s_cbranch_scc0 .Lcf_skip_4_29
	s_add_u32 s100, s68, 0x16354c40
	s_addc_u32 s101, s69, 0
	global_store_dword v21, v26, s[100:101]
.Lcf_skip_4_29:
	v_fma_f32 v26, v112, v26, v113
	s_cmp_eq_u32 s99, 5
	s_cbranch_scc0 .Lcf_skip_4_30
	s_add_u32 s100, s68, 0x16353c40
	s_addc_u32 s101, s69, 0
	global_store_dword v21, v26, s[100:101]
.Lcf_skip_4_30:
	v_fma_f32 v26, v114, v26, v115
	s_cmp_eq_u32 s99, 4
	s_cbranch_scc0 .Lcf_skip_4_31
	s_add_u32 s100, s68, 0x16352c40
	s_addc_u32 s101, s69, 0
	global_store_dword v21, v26, s[100:101]
.Lcf_skip_4_31:
	v_fma_f32 v26, v116, v26, v117
	s_cmp_eq_u32 s99, 3
	s_cbranch_scc0 .Lcf_skip_4_32
	s_add_u32 s100, s68, 0x16351c40
	s_addc_u32 s101, s69, 0
	global_store_dword v21, v26, s[100:101]

.Lcf_var_5:
	s_add_u32 s100, s68, 0x1622cc40
	s_addc_u32 s101, s69, 0
	global_load_dwordx2 v[48:49], v20, s[100:101]
	s_add_u32 s100, s68, 0x1622ac40
	s_addc_u32 s101, s69, 0
	global_load_dwordx2 v[50:51], v20, s[100:101]
	s_add_u32 s100, s68, 0x16228c40
	s_addc_u32 s101, s69, 0
	global_load_dwordx2 v[52:53], v20, s[100:101]
	s_add_u32 s100, s68, 0x16226c40
	s_addc_u32 s101, s69, 0
	global_load_dwordx2 v[54:55], v20, s[100:101]
	s_add_u32 s100, s68, 0x16224c40
	s_addc_u32 s101, s69, 0
	global_load_dwordx2 v[56:57], v20, s[100:101]
	s_add_u32 s100, s68, 0x16222c40
	s_addc_u32 s101, s69, 0
	global_load_dwordx2 v[58:59], v20, s[100:101]
	s_add_u32 s100, s68, 0x16220c40
	s_addc_u32 s101, s69, 0
	global_load_dwordx2 v[60:61], v20, s[100:101]
	s_add_u32 s100, s68, 0x1621ec40
	s_addc_u32 s101, s69, 0
	global_load_dwordx2 v[62:63], v20, s[100:101]
	s_add_u32 s100, s68, 0x1621cc40
	s_addc_u32 s101, s69, 0
	global_load_dwordx2 v[64:65], v20, s[100:101]
	s_add_u32 s100, s68, 0x1621ac40
	s_addc_u32 s101, s69, 0
	global_load_dwordx2 v[66:67], v20, s[100:101]
	s_add_u32 s100, s68, 0x16218c40
	s_addc_u32 s101, s69, 0
	global_load_dwordx2 v[68:69], v20, s[100:101]
	s_add_u32 s100, s68, 0x16216c40
	s_addc_u32 s101, s69, 0
	global_load_dwordx2 v[70:71], v20, s[100:101]
	s_add_u32 s100, s68, 0x16214c40
	s_addc_u32 s101, s69, 0
	global_load_dwordx2 v[78:79], v20, s[100:101]
	s_add_u32 s100, s68, 0x16212c40
	s_addc_u32 s101, s69, 0
	global_load_dwordx2 v[80:81], v20, s[100:101]
	s_add_u32 s100, s68, 0x16210c40
	s_addc_u32 s101, s69, 0
	global_load_dwordx2 v[82:83], v20, s[100:101]
	s_add_u32 s100, s68, 0x1620ec40
	s_addc_u32 s101, s69, 0
	global_load_dwordx2 v[84:85], v20, s[100:101]
	s_add_u32 s100, s68, 0x1620cc40
	s_addc_u32 s101, s69, 0
	global_load_dwordx2 v[86:87], v20, s[100:101]
	s_add_u32 s100, s68, 0x1620ac40
	s_addc_u32 s101, s69, 0
	global_load_dwordx2 v[88:89], v20, s[100:101]
	s_add_u32 s100, s68, 0x16208c40
	s_addc_u32 s101, s69, 0
	global_load_dwordx2 v[90:91], v20, s[100:101]
	s_add_u32 s100, s68, 0x16206c40
	s_addc_u32 s101, s69, 0
	global_load_dwordx2 v[92:93], v20, s[100:101]
	s_add_u32 s100, s68, 0x16204c40
	s_addc_u32 s101, s69, 0
	global_load_dwordx2 v[94:95], v20, s[100:101]
	s_add_u32 s100, s68, 0x16202c40
	s_addc_u32 s101, s69, 0
	global_load_dwordx2 v[96:97], v20, s[100:101]
	s_add_u32 s100, s68, 0x16200c40
	s_addc_u32 s101, s69, 0
	global_load_dwordx2 v[98:99], v20, s[100:101]
	s_add_u32 s100, s68, 0x161fec40
	s_addc_u32 s101, s69, 0
	global_load_dwordx2 v[100:101], v20, s[100:101]
	s_add_u32 s100, s68, 0x161fcc40
	s_addc_u32 s101, s69, 0
	global_load_dwordx2 v[102:103], v20, s[100:101]
	s_add_u32 s100, s68, 0x161fac40
	s_addc_u32 s101, s69, 0
	global_load_dwordx2 v[104:105], v20, s[100:101]
	s_add_u32 s100, s68, 0x161f8c40
	s_addc_u32 s101, s69, 0
	global_load_dwordx2 v[106:107], v20, s[100:101]
	s_add_u32 s100, s68, 0x161f6c40
	s_addc_u32 s101, s69, 0
	global_load_dwordx2 v[108:109], v20, s[100:101]
	s_add_u32 s100, s68, 0x161f4c40
	s_addc_u32 s101, s69, 0
	global_load_dwordx2 v[110:111], v20, s[100:101]
	s_add_u32 s100, s68, 0x161f2c40
	s_addc_u32 s101, s69, 0
	global_load_dwordx2 v[112:113], v20, s[100:101]
	s_add_u32 s100, s68, 0x161f0c40
	s_addc_u32 s101, s69, 0
	global_load_dwordx2 v[114:115], v20, s[100:101]
	s_add_u32 s100, s68, 0x161eec40
	s_addc_u32 s101, s69, 0
	global_load_dwordx2 v[116:117], v20, s[100:101]
	s_add_u32 s100, s68, 0x161ecc40
	s_addc_u32 s101, s69, 0
	global_load_dwordx2 v[118:119], v20, s[100:101]
	v_mov_b32_e32 v24, 1.0
	v_mov_b32_e32 v25, 0
	s_waitcnt vmcnt(32)
	v_fma_f32 v25, v48, v25, v49
	v_mul_f32_e32 v24, v24, v48
	s_waitcnt vmcnt(31)
	v_fma_f32 v25, v50, v25, v51
	v_mul_f32_e32 v24, v24, v50
	s_waitcnt vmcnt(30)
	v_fma_f32 v25, v52, v25, v53
	v_mul_f32_e32 v24, v24, v52
	s_waitcnt vmcnt(29)
	v_fma_f32 v25, v54, v25, v55
	v_mul_f32_e32 v24, v24, v54
	s_waitcnt vmcnt(28)
	v_fma_f32 v25, v56, v25, v57
	v_mul_f32_e32 v24, v24, v56
	s_waitcnt vmcnt(27)
	v_fma_f32 v25, v58, v25, v59
	v_mul_f32_e32 v24, v24, v58
	s_waitcnt vmcnt(26)
	v_fma_f32 v25, v60, v25, v61
	v_mul_f32_e32 v24, v24, v60
	s_waitcnt vmcnt(25)
	v_fma_f32 v25, v62, v25, v63
	v_mul_f32_e32 v24, v24, v62
	s_waitcnt vmcnt(24)
	v_fma_f32 v25, v64, v25, v65
	v_mul_f32_e32 v24, v24, v64
	s_waitcnt vmcnt(23)
	v_fma_f32 v25, v66, v25, v67
	v_mul_f32_e32 v24, v24, v66
	s_waitcnt vmcnt(22)
	v_fma_f32 v25, v68, v25, v69
	v_mul_f32_e32 v24, v24, v68
	s_waitcnt vmcnt(21)
	v_fma_f32 v25, v70, v25, v71
	v_mul_f32_e32 v24, v24, v70
	s_waitcnt vmcnt(20)
	v_fma_f32 v25, v78, v25, v79
	v_mul_f32_e32 v24, v24, v78
	s_waitcnt vmcnt(19)
	v_fma_f32 v25, v80, v25, v81
	v_mul_f32_e32 v24, v24, v80
	s_waitcnt vmcnt(18)
	v_fma_f32 v25, v82, v25, v83
	v_mul_f32_e32 v24, v24, v82
	s_waitcnt vmcnt(17)
	v_fma_f32 v25, v84, v25, v85
	v_mul_f32_e32 v24, v24, v84
	s_waitcnt vmcnt(16)
	v_fma_f32 v25, v86, v25, v87
	v_mul_f32_e32 v24, v24, v86
	s_waitcnt vmcnt(15)
	v_fma_f32 v25, v88, v25, v89
	v_mul_f32_e32 v24, v24, v88
	s_waitcnt vmcnt(14)
	v_fma_f32 v25, v90, v25, v91
	v_mul_f32_e32 v24, v24, v90
	s_waitcnt vmcnt(13)
	v_fma_f32 v25, v92, v25, v93
	v_mul_f32_e32 v24, v24, v92
	s_waitcnt vmcnt(12)
	v_fma_f32 v25, v94, v25, v95
	v_mul_f32_e32 v24, v24, v94
	s_waitcnt vmcnt(11)
	v_fma_f32 v25, v96, v25, v97
	v_mul_f32_e32 v24, v24, v96
	s_waitcnt vmcnt(10)
	v_fma_f32 v25, v98, v25, v99
	v_mul_f32_e32 v24, v24, v98
	s_waitcnt vmcnt(9)
	v_fma_f32 v25, v100, v25, v101
	v_mul_f32_e32 v24, v24, v100
	s_waitcnt vmcnt(8)
	v_fma_f32 v25, v102, v25, v103
	v_mul_f32_e32 v24, v24, v102
	s_waitcnt vmcnt(7)
	v_fma_f32 v25, v104, v25, v105
	v_mul_f32_e32 v24, v24, v104
	s_waitcnt vmcnt(6)
	v_fma_f32 v25, v106, v25, v107
	v_mul_f32_e32 v24, v24, v106
	s_waitcnt vmcnt(5)
	v_fma_f32 v25, v108, v25, v109
	v_mul_f32_e32 v24, v24, v108
	s_waitcnt vmcnt(4)
	v_fma_f32 v25, v110, v25, v111
	v_mul_f32_e32 v24, v24, v110
	s_waitcnt vmcnt(3)
	v_fma_f32 v25, v112, v25, v113
	v_mul_f32_e32 v24, v24, v112
	s_waitcnt vmcnt(2)
	v_fma_f32 v25, v114, v25, v115
	v_mul_f32_e32 v24, v24, v114
	s_waitcnt vmcnt(1)
	v_fma_f32 v25, v116, v25, v117
	v_mul_f32_e32 v24, v24, v116
	s_waitcnt vmcnt(0)
	v_fma_f32 v25, v118, v25, v119
	v_mul_f32_e32 v24, v24, v118
	ds_write_b64 v22, v[24:25] offset:2560
	s_waitcnt lgkmcnt(0)
	s_barrier
	v_mov_b32_e32 v26, 0
	ds_read_b64 v[28:29], v22 offset:2048
	s_waitcnt lgkmcnt(0)
	v_fma_f32 v26, v28, v26, v29
	s_cmp_eq_u32 s99, 2
	s_cbranch_scc0 .Lcf_skip_5_0
	s_add_u32 s100, s68, 0x16350c40
	s_addc_u32 s101, s69, 0
	global_store_dword v21, v26, s[100:101]
.Lcf_skip_5_0:
	v_fma_f32 v26, v48, v26, v49
	s_cmp_eq_u32 s99, 1
	s_cbranch_scc0 .Lcf_skip_5_1
	s_add_u32 s100, s68, 0x1634fc40
	s_addc_u32 s101, s69, 0
	global_store_dword v21, v26, s[100:101]
.Lcf_skip_5_1:
	v_fma_f32 v26, v50, v26, v51
	s_cmp_eq_u32 s99, 0
	s_cbranch_scc0 .Lcf_skip_5_2
	s_add_u32 s100, s68, 0x1634ec40
	s_addc_u32 s101, s69, 0
	global_store_dword v21, v26, s[100:101]
.Lcf_skip_5_2:
	v_fma_f32 v26, v52, v26, v53
	s_cmp_eq_u32 s99, 15
	s_cbranch_scc0 .Lcf_skip_5_3
	s_add_u32 s100, s68, 0x1634dc40
	s_addc_u32 s101, s69, 0
	global_store_dword v21, v26, s[100:101]
.Lcf_skip_5_3:
	v_fma_f32 v26, v54, v26, v55
	s_cmp_eq_u32 s99, 14
	s_cbranch_scc0 .Lcf_skip_5_4
	s_add_u32 s100, s68, 0x1634cc40
	s_addc_u32 s101, s69, 0
	global_store_dword v21, v26, s[100:101]
.Lcf_skip_5_4:
	v_fma_f32 v26, v56, v26, v57
	s_cmp_eq_u32 s99, 13
	s_cbranch_scc0 .Lcf_skip_5_5
	s_add_u32 s100, s68, 0x1634bc40
	s_addc_u32 s101, s69, 0
	global_store_dword v21, v26, s[100:101]
.Lcf_skip_5_5:
	v_fma_f32 v26, v58, v26, v59
	s_cmp_eq_u32 s99, 12
	s_cbranch_scc0 .Lcf_skip_5_6
	s_add_u32 s100, s68, 0x1634ac40
	s_addc_u32 s101, s69, 0
	global_store_dword v21, v26, s[100:101]
.Lcf_skip_5_6:
	v_fma_f32 v26, v60, v26, v61
	s_cmp_eq_u32 s99, 11
	s_cbranch_scc0 .Lcf_skip_5_7
	s_add_u32 s100, s68, 0x16349c40
	s_addc_u32 s101, s69, 0
	global_store_dword v21, v26, s[100:101]
.Lcf_skip_5_7:
	v_fma_f32 v26, v62, v26, v63
	s_cmp_eq_u32 s99, 10
	s_cbranch_scc0 .Lcf_skip_5_8
	s_add_u32 s100, s68, 0x16348c40
	s_addc_u32 s101, s69, 0
	global_store_dword v21, v26, s[100:101]
.Lcf_skip_5_8:
	v_fma_f32 v26, v64, v26, v65
	s_cmp_eq_u32 s99, 9
	s_cbranch_scc0 .Lcf_skip_5_9
	s_add_u32 s100, s68, 0x16347c40
	s_addc_u32 s101, s69, 0
	global_store_dword v21, v26, s[100:101]
.Lcf_skip_5_9:
	v_fma_f32 v26, v66, v26, v67
	s_cmp_eq_u32 s99, 8
	s_cbranch_scc0 .Lcf_skip_5_10
	s_add_u32 s100, s68, 0x16346c40
	s_addc_u32 s101, s69, 0
	global_store_dword v21, v26, s[100:101]
.Lcf_skip_5_10:
	v_fma_f32 v26, v68, v26, v69
	s_cmp_eq_u32 s99, 7
	s_cbranch_scc0 .Lcf_skip_5_11
	s_add_u32 s100, s68, 0x16345c40
	s_addc_u32 s101, s69, 0
	global_store_dword v21, v26, s[100:101]
.Lcf_skip_5_11:
	v_fma_f32 v26, v70, v26, v71
	s_cmp_eq_u32 s99, 6
	s_cbranch_scc0 .Lcf_skip_5_12
	s_add_u32 s100, s68, 0x16344c40
	s_addc_u32 s101, s69, 0
	global_store_dword v21, v26, s[100:101]
.Lcf_skip_5_12:
	v_fma_f32 v26, v78, v26, v79
	s_cmp_eq_u32 s99, 5
	s_cbranch_scc0 .Lcf_skip_5_13
	s_add_u32 s100, s68, 0x16343c40
	s_addc_u32 s101, s69, 0
	global_store_dword v21, v26, s[100:101]
.Lcf_skip_5_13:
	v_fma_f32 v26, v80, v26, v81
	s_cmp_eq_u32 s99, 4
	s_cbranch_scc0 .Lcf_skip_5_14
	s_add_u32 s100, s68, 0x16342c40
	s_addc_u32 s101, s69, 0
	global_store_dword v21, v26, s[100:101]
.Lcf_skip_5_14:
	v_fma_f32 v26, v82, v26, v83
	s_cmp_eq_u32 s99, 3
	s_cbranch_scc0 .Lcf_skip_5_15
	s_add_u32 s100, s68, 0x16341c40
	s_addc_u32 s101, s69, 0
	global_store_dword v21, v26, s[100:101]
.Lcf_skip_5_15:
	v_fma_f32 v26, v84, v26, v85
	s_cmp_eq_u32 s99, 2
	s_cbranch_scc0 .Lcf_skip_5_16
	s_add_u32 s100, s68, 0x16340c40
	s_addc_u32 s101, s69, 0
	global_store_dword v21, v26, s[100:101]
.Lcf_skip_5_16:
	v_fma_f32 v26, v86, v26, v87
	s_cmp_eq_u32 s99, 1
	s_cbranch_scc0 .Lcf_skip_5_17
	s_add_u32 s100, s68, 0x1633fc40
	s_addc_u32 s101, s69, 0
	global_store_dword v21, v26, s[100:101]
.Lcf_skip_5_17:
	v_fma_f32 v26, v88, v26, v89
	s_cmp_eq_u32 s99, 0
	s_cbranch_scc0 .Lcf_skip_5_18
	s_add_u32 s100, s68, 0x1633ec40
	s_addc_u32 s101, s69, 0
	global_store_dword v21, v26, s[100:101]
.Lcf_skip_5_18:
	v_fma_f32 v26, v90, v26, v91
	s_cmp_eq_u32 s99, 15
	s_cbranch_scc0 .Lcf_skip_5_19
	s_add_u32 s100, s68, 0x1633dc40
	s_addc_u32 s101, s69, 0
	global_store_dword v21, v26, s[100:101]
.Lcf_skip_5_19:
	v_fma_f32 v26, v92, v26, v93
	s_cmp_eq_u32 s99, 14
	s_cbranch_scc0 .Lcf_skip_5_20
	s_add_u32 s100, s68, 0x1633cc40
	s_addc_u32 s101, s69, 0
	global_store_dword v21, v26, s[100:101]
.Lcf_skip_5_20:
	v_fma_f32 v26, v94, v26, v95
	s_cmp_eq_u32 s99, 13
	s_cbranch_scc0 .Lcf_skip_5_21
	s_add_u32 s100, s68, 0x1633bc40
	s_addc_u32 s101, s69, 0
	global_store_dword v21, v26, s[100:101]
.Lcf_skip_5_21:
	v_fma_f32 v26, v96, v26, v97
	s_cmp_eq_u32 s99, 12
	s_cbranch_scc0 .Lcf_skip_5_22
	s_add_u32 s100, s68, 0x1633ac40
	s_addc_u32 s101, s69, 0
	global_store_dword v21, v26, s[100:101]
.Lcf_skip_5_22:
	v_fma_f32 v26, v98, v26, v99
	s_cmp_eq_u32 s99, 11
	s_cbranch_scc0 .Lcf_skip_5_23
	s_add_u32 s100, s68, 0x16339c40
	s_addc_u32 s101, s69, 0
	global_store_dword v21, v26, s[100:101]
.Lcf_skip_5_23:
	v_fma_f32 v26, v100, v26, v101
	s_cmp_eq_u32 s99, 10
	s_cbranch_scc0 .Lcf_skip_5_24
	s_add_u32 s100, s68, 0x16338c40
	s_addc_u32 s101, s69, 0
	global_store_dword v21, v26, s[100:101]
.Lcf_skip_5_24:
	v_fma_f32 v26, v102, v26, v103
	s_cmp_eq_u32 s99, 9
	s_cbranch_scc0 .Lcf_skip_5_25
	s_add_u32 s100, s68, 0x16337c40
	s_addc_u32 s101, s69, 0
	global_store_dword v21, v26, s[100:101]
.Lcf_skip_5_25:
	v_fma_f32 v26, v104, v26, v105
	s_cmp_eq_u32 s99, 8
	s_cbranch_scc0 .Lcf_skip_5_26
	s_add_u32 s100, s68, 0x16336c40
	s_addc_u32 s101, s69, 0
	global_store_dword v21, v26, s[100:101]
.Lcf_skip_5_26:
	v_fma_f32 v26, v106, v26, v107
	s_cmp_eq_u32 s99, 7
	s_cbranch_scc0 .Lcf_skip_5_27
	s_add_u32 s100, s68, 0x16335c40
	s_addc_u32 s101, s69, 0
	global_store_dword v21, v26, s[100:101]
.Lcf_skip_5_27:
	v_fma_f32 v26, v108, v26, v109
	s_cmp_eq_u32 s99, 6
	s_cbranch_scc0 .Lcf_skip_5_28
	s_add_u32 s100, s68, 0x16334c40
	s_addc_u32 s101, s69, 0
	global_store_dword v21, v26, s[100:101]
.Lcf_skip_5_28:
	v_fma_f32 v26, v110, v26, v111
	s_cmp_eq_u32 s99, 5
	s_cbranch_scc0 .Lcf_skip_5_29
	s_add_u32 s100, s68, 0x16333c40
	s_addc_u32 s101, s69, 0
	global_store_dword v21, v26, s[100:101]
.Lcf_skip_5_29:
	v_fma_f32 v26, v112, v26, v113
	s_cmp_eq_u32 s99, 4
	s_cbranch_scc0 .Lcf_skip_5_30
	s_add_u32 s100, s68, 0x16332c40
	s_addc_u32 s101, s69, 0
	global_store_dword v21, v26, s[100:101]
.Lcf_skip_5_30:
	v_fma_f32 v26, v114, v26, v115
	s_cmp_eq_u32 s99, 3
	s_cbranch_scc0 .Lcf_skip_5_31
	s_add_u32 s100, s68, 0x16331c40
	s_addc_u32 s101, s69, 0
	global_store_dword v21, v26, s[100:101]
.Lcf_skip_5_31:
	v_fma_f32 v26, v116, v26, v117
	s_cmp_eq_u32 s99, 2
	s_cbranch_scc0 .Lcf_skip_5_32
	s_add_u32 s100, s68, 0x16330c40
	s_addc_u32 s101, s69, 0
	global_store_dword v21, v26, s[100:101]

.Lcf_var_6:
	s_add_u32 s100, s68, 0x161eac40
	s_addc_u32 s101, s69, 0
	global_load_dwordx2 v[48:49], v20, s[100:101]
	s_add_u32 s100, s68, 0x161e8c40
	s_addc_u32 s101, s69, 0
	global_load_dwordx2 v[50:51], v20, s[100:101]
	s_add_u32 s100, s68, 0x161e6c40
	s_addc_u32 s101, s69, 0
	global_load_dwordx2 v[52:53], v20, s[100:101]
	s_add_u32 s100, s68, 0x161e4c40
	s_addc_u32 s101, s69, 0
	global_load_dwordx2 v[54:55], v20, s[100:101]
	s_add_u32 s100, s68, 0x161e2c40
	s_addc_u32 s101, s69, 0
	global_load_dwordx2 v[56:57], v20, s[100:101]
	s_add_u32 s100, s68, 0x161e0c40
	s_addc_u32 s101, s69, 0
	global_load_dwordx2 v[58:59], v20, s[100:101]
	s_add_u32 s100, s68, 0x161dec40
	s_addc_u32 s101, s69, 0
	global_load_dwordx2 v[60:61], v20, s[100:101]
	s_add_u32 s100, s68, 0x161dcc40
	s_addc_u32 s101, s69, 0
	global_load_dwordx2 v[62:63], v20, s[100:101]
	s_add_u32 s100, s68, 0x161dac40
	s_addc_u32 s101, s69, 0
	global_load_dwordx2 v[64:65], v20, s[100:101]
	s_add_u32 s100, s68, 0x161d8c40
	s_addc_u32 s101, s69, 0
	global_load_dwordx2 v[66:67], v20, s[100:101]
	s_add_u32 s100, s68, 0x161d6c40
	s_addc_u32 s101, s69, 0
	global_load_dwordx2 v[68:69], v20, s[100:101]
	s_add_u32 s100, s68, 0x161d4c40
	s_addc_u32 s101, s69, 0
	global_load_dwordx2 v[70:71], v20, s[100:101]
	s_add_u32 s100, s68, 0x161d2c40
	s_addc_u32 s101, s69, 0
	global_load_dwordx2 v[78:79], v20, s[100:101]
	s_add_u32 s100, s68, 0x161d0c40
	s_addc_u32 s101, s69, 0
	global_load_dwordx2 v[80:81], v20, s[100:101]
	s_add_u32 s100, s68, 0x161cec40
	s_addc_u32 s101, s69, 0
	global_load_dwordx2 v[82:83], v20, s[100:101]
	s_add_u32 s100, s68, 0x161ccc40
	s_addc_u32 s101, s69, 0
	global_load_dwordx2 v[84:85], v20, s[100:101]
	s_add_u32 s100, s68, 0x161cac40
	s_addc_u32 s101, s69, 0
	global_load_dwordx2 v[86:87], v20, s[100:101]
	s_add_u32 s100, s68, 0x161c8c40
	s_addc_u32 s101, s69, 0
	global_load_dwordx2 v[88:89], v20, s[100:101]
	s_add_u32 s100, s68, 0x161c6c40
	s_addc_u32 s101, s69, 0
	global_load_dwordx2 v[90:91], v20, s[100:101]
	s_add_u32 s100, s68, 0x161c4c40
	s_addc_u32 s101, s69, 0
	global_load_dwordx2 v[92:93], v20, s[100:101]
	s_add_u32 s100, s68, 0x161c2c40
	s_addc_u32 s101, s69, 0
	global_load_dwordx2 v[94:95], v20, s[100:101]
	s_add_u32 s100, s68, 0x161c0c40
	s_addc_u32 s101, s69, 0
	global_load_dwordx2 v[96:97], v20, s[100:101]
	s_add_u32 s100, s68, 0x161bec40
	s_addc_u32 s101, s69, 0
	global_load_dwordx2 v[98:99], v20, s[100:101]
	s_add_u32 s100, s68, 0x161bcc40
	s_addc_u32 s101, s69, 0
	global_load_dwordx2 v[100:101], v20, s[100:101]
	s_add_u32 s100, s68, 0x161bac40
	s_addc_u32 s101, s69, 0
	global_load_dwordx2 v[102:103], v20, s[100:101]
	s_add_u32 s100, s68, 0x161b8c40
	s_addc_u32 s101, s69, 0
	global_load_dwordx2 v[104:105], v20, s[100:101]
	s_add_u32 s100, s68, 0x161b6c40
	s_addc_u32 s101, s69, 0
	global_load_dwordx2 v[106:107], v20, s[100:101]
	s_add_u32 s100, s68, 0x161b4c40
	s_addc_u32 s101, s69, 0
	global_load_dwordx2 v[108:109], v20, s[100:101]
	s_add_u32 s100, s68, 0x161b2c40
	s_addc_u32 s101, s69, 0
	global_load_dwordx2 v[110:111], v20, s[100:101]
	s_add_u32 s100, s68, 0x161b0c40
	s_addc_u32 s101, s69, 0
	global_load_dwordx2 v[112:113], v20, s[100:101]
	s_add_u32 s100, s68, 0x161aec40
	s_addc_u32 s101, s69, 0
	global_load_dwordx2 v[114:115], v20, s[100:101]
	s_add_u32 s100, s68, 0x161acc40
	s_addc_u32 s101, s69, 0
	global_load_dwordx2 v[116:117], v20, s[100:101]
	s_add_u32 s100, s68, 0x161aac40
	s_addc_u32 s101, s69, 0
	global_load_dwordx2 v[118:119], v20, s[100:101]
	v_mov_b32_e32 v24, 1.0
	v_mov_b32_e32 v25, 0
	s_waitcnt vmcnt(32)
	v_fma_f32 v25, v48, v25, v49
	v_mul_f32_e32 v24, v24, v48
	s_waitcnt vmcnt(31)
	v_fma_f32 v25, v50, v25, v51
	v_mul_f32_e32 v24, v24, v50
	s_waitcnt vmcnt(30)
	v_fma_f32 v25, v52, v25, v53
	v_mul_f32_e32 v24, v24, v52
	s_waitcnt vmcnt(29)
	v_fma_f32 v25, v54, v25, v55
	v_mul_f32_e32 v24, v24, v54
	s_waitcnt vmcnt(28)
	v_fma_f32 v25, v56, v25, v57
	v_mul_f32_e32 v24, v24, v56
	s_waitcnt vmcnt(27)
	v_fma_f32 v25, v58, v25, v59
	v_mul_f32_e32 v24, v24, v58
	s_waitcnt vmcnt(26)
	v_fma_f32 v25, v60, v25, v61
	v_mul_f32_e32 v24, v24, v60
	s_waitcnt vmcnt(25)
	v_fma_f32 v25, v62, v25, v63
	v_mul_f32_e32 v24, v24, v62
	s_waitcnt vmcnt(24)
	v_fma_f32 v25, v64, v25, v65
	v_mul_f32_e32 v24, v24, v64
	s_waitcnt vmcnt(23)
	v_fma_f32 v25, v66, v25, v67
	v_mul_f32_e32 v24, v24, v66
	s_waitcnt vmcnt(22)
	v_fma_f32 v25, v68, v25, v69
	v_mul_f32_e32 v24, v24, v68
	s_waitcnt vmcnt(21)
	v_fma_f32 v25, v70, v25, v71
	v_mul_f32_e32 v24, v24, v70
	s_waitcnt vmcnt(20)
	v_fma_f32 v25, v78, v25, v79
	v_mul_f32_e32 v24, v24, v78
	s_waitcnt vmcnt(19)
	v_fma_f32 v25, v80, v25, v81
	v_mul_f32_e32 v24, v24, v80
	s_waitcnt vmcnt(18)
	v_fma_f32 v25, v82, v25, v83
	v_mul_f32_e32 v24, v24, v82
	s_waitcnt vmcnt(17)
	v_fma_f32 v25, v84, v25, v85
	v_mul_f32_e32 v24, v24, v84
	s_waitcnt vmcnt(16)
	v_fma_f32 v25, v86, v25, v87
	v_mul_f32_e32 v24, v24, v86
	s_waitcnt vmcnt(15)
	v_fma_f32 v25, v88, v25, v89
	v_mul_f32_e32 v24, v24, v88
	s_waitcnt vmcnt(14)
	v_fma_f32 v25, v90, v25, v91
	v_mul_f32_e32 v24, v24, v90
	s_waitcnt vmcnt(13)
	v_fma_f32 v25, v92, v25, v93
	v_mul_f32_e32 v24, v24, v92
	s_waitcnt vmcnt(12)
	v_fma_f32 v25, v94, v25, v95
	v_mul_f32_e32 v24, v24, v94
	s_waitcnt vmcnt(11)
	v_fma_f32 v25, v96, v25, v97
	v_mul_f32_e32 v24, v24, v96
	s_waitcnt vmcnt(10)
	v_fma_f32 v25, v98, v25, v99
	v_mul_f32_e32 v24, v24, v98
	s_waitcnt vmcnt(9)
	v_fma_f32 v25, v100, v25, v101
	v_mul_f32_e32 v24, v24, v100
	s_waitcnt vmcnt(8)
	v_fma_f32 v25, v102, v25, v103
	v_mul_f32_e32 v24, v24, v102
	s_waitcnt vmcnt(7)
	v_fma_f32 v25, v104, v25, v105
	v_mul_f32_e32 v24, v24, v104
	s_waitcnt vmcnt(6)
	v_fma_f32 v25, v106, v25, v107
	v_mul_f32_e32 v24, v24, v106
	s_waitcnt vmcnt(5)
	v_fma_f32 v25, v108, v25, v109
	v_mul_f32_e32 v24, v24, v108
	s_waitcnt vmcnt(4)
	v_fma_f32 v25, v110, v25, v111
	v_mul_f32_e32 v24, v24, v110
	s_waitcnt vmcnt(3)
	v_fma_f32 v25, v112, v25, v113
	v_mul_f32_e32 v24, v24, v112
	s_waitcnt vmcnt(2)
	v_fma_f32 v25, v114, v25, v115
	v_mul_f32_e32 v24, v24, v114
	s_waitcnt vmcnt(1)
	v_fma_f32 v25, v116, v25, v117
	v_mul_f32_e32 v24, v24, v116
	s_waitcnt vmcnt(0)
	v_fma_f32 v25, v118, v25, v119
	v_mul_f32_e32 v24, v24, v118
	ds_write_b64 v22, v[24:25] offset:3072
	s_waitcnt lgkmcnt(0)
	s_barrier
	v_mov_b32_e32 v26, 0
	ds_read_b64 v[28:29], v22 offset:2048
	s_waitcnt lgkmcnt(0)
	v_fma_f32 v26, v28, v26, v29
	ds_read_b64 v[28:29], v22 offset:2560
	s_waitcnt lgkmcnt(0)
	v_fma_f32 v26, v28, v26, v29
	s_cmp_eq_u32 s99, 1
	s_cbranch_scc0 .Lcf_skip_6_0
	s_add_u32 s100, s68, 0x1632fc40
	s_addc_u32 s101, s69, 0
	global_store_dword v21, v26, s[100:101]
.Lcf_skip_6_0:
	v_fma_f32 v26, v48, v26, v49
	s_cmp_eq_u32 s99, 0
	s_cbranch_scc0 .Lcf_skip_6_1
	s_add_u32 s100, s68, 0x1632ec40
	s_addc_u32 s101, s69, 0
	global_store_dword v21, v26, s[100:101]
.Lcf_skip_6_1:
	v_fma_f32 v26, v50, v26, v51
	s_cmp_eq_u32 s99, 15
	s_cbranch_scc0 .Lcf_skip_6_2
	s_add_u32 s100, s68, 0x1632dc40
	s_addc_u32 s101, s69, 0
	global_store_dword v21, v26, s[100:101]
.Lcf_skip_6_2:
	v_fma_f32 v26, v52, v26, v53
	s_cmp_eq_u32 s99, 14
	s_cbranch_scc0 .Lcf_skip_6_3
	s_add_u32 s100, s68, 0x1632cc40
	s_addc_u32 s101, s69, 0
	global_store_dword v21, v26, s[100:101]
.Lcf_skip_6_3:
	v_fma_f32 v26, v54, v26, v55
	s_cmp_eq_u32 s99, 13
	s_cbranch_scc0 .Lcf_skip_6_4
	s_add_u32 s100, s68, 0x1632bc40
	s_addc_u32 s101, s69, 0
	global_store_dword v21, v26, s[100:101]
.Lcf_skip_6_4:
	v_fma_f32 v26, v56, v26, v57
	s_cmp_eq_u32 s99, 12
	s_cbranch_scc0 .Lcf_skip_6_5
	s_add_u32 s100, s68, 0x1632ac40
	s_addc_u32 s101, s69, 0
	global_store_dword v21, v26, s[100:101]
.Lcf_skip_6_5:
	v_fma_f32 v26, v58, v26, v59
	s_cmp_eq_u32 s99, 11
	s_cbranch_scc0 .Lcf_skip_6_6
	s_add_u32 s100, s68, 0x16329c40
	s_addc_u32 s101, s69, 0
	global_store_dword v21, v26, s[100:101]
.Lcf_skip_6_6:
	v_fma_f32 v26, v60, v26, v61
	s_cmp_eq_u32 s99, 10
	s_cbranch_scc0 .Lcf_skip_6_7
	s_add_u32 s100, s68, 0x16328c40
	s_addc_u32 s101, s69, 0
	global_store_dword v21, v26, s[100:101]
.Lcf_skip_6_7:
	v_fma_f32 v26, v62, v26, v63
	s_cmp_eq_u32 s99, 9
	s_cbranch_scc0 .Lcf_skip_6_8
	s_add_u32 s100, s68, 0x16327c40
	s_addc_u32 s101, s69, 0
	global_store_dword v21, v26, s[100:101]
.Lcf_skip_6_8:
	v_fma_f32 v26, v64, v26, v65
	s_cmp_eq_u32 s99, 8
	s_cbranch_scc0 .Lcf_skip_6_9
	s_add_u32 s100, s68, 0x16326c40
	s_addc_u32 s101, s69, 0
	global_store_dword v21, v26, s[100:101]
.Lcf_skip_6_9:
	v_fma_f32 v26, v66, v26, v67
	s_cmp_eq_u32 s99, 7
	s_cbranch_scc0 .Lcf_skip_6_10
	s_add_u32 s100, s68, 0x16325c40
	s_addc_u32 s101, s69, 0
	global_store_dword v21, v26, s[100:101]
.Lcf_skip_6_10:
	v_fma_f32 v26, v68, v26, v69
	s_cmp_eq_u32 s99, 6
	s_cbranch_scc0 .Lcf_skip_6_11
	s_add_u32 s100, s68, 0x16324c40
	s_addc_u32 s101, s69, 0
	global_store_dword v21, v26, s[100:101]
.Lcf_skip_6_11:
	v_fma_f32 v26, v70, v26, v71
	s_cmp_eq_u32 s99, 5
	s_cbranch_scc0 .Lcf_skip_6_12
	s_add_u32 s100, s68, 0x16323c40
	s_addc_u32 s101, s69, 0
	global_store_dword v21, v26, s[100:101]
.Lcf_skip_6_12:
	v_fma_f32 v26, v78, v26, v79
	s_cmp_eq_u32 s99, 4
	s_cbranch_scc0 .Lcf_skip_6_13
	s_add_u32 s100, s68, 0x16322c40
	s_addc_u32 s101, s69, 0
	global_store_dword v21, v26, s[100:101]
.Lcf_skip_6_13:
	v_fma_f32 v26, v80, v26, v81
	s_cmp_eq_u32 s99, 3
	s_cbranch_scc0 .Lcf_skip_6_14
	s_add_u32 s100, s68, 0x16321c40
	s_addc_u32 s101, s69, 0
	global_store_dword v21, v26, s[100:101]
.Lcf_skip_6_14:
	v_fma_f32 v26, v82, v26, v83
	s_cmp_eq_u32 s99, 2
	s_cbranch_scc0 .Lcf_skip_6_15
	s_add_u32 s100, s68, 0x16320c40
	s_addc_u32 s101, s69, 0
	global_store_dword v21, v26, s[100:101]
.Lcf_skip_6_15:
	v_fma_f32 v26, v84, v26, v85
	s_cmp_eq_u32 s99, 1
	s_cbranch_scc0 .Lcf_skip_6_16
	s_add_u32 s100, s68, 0x1631fc40
	s_addc_u32 s101, s69, 0
	global_store_dword v21, v26, s[100:101]
.Lcf_skip_6_16:
	v_fma_f32 v26, v86, v26, v87
	s_cmp_eq_u32 s99, 0
	s_cbranch_scc0 .Lcf_skip_6_17
	s_add_u32 s100, s68, 0x1631ec40
	s_addc_u32 s101, s69, 0
	global_store_dword v21, v26, s[100:101]
.Lcf_skip_6_17:
	v_fma_f32 v26, v88, v26, v89
	s_cmp_eq_u32 s99, 15
	s_cbranch_scc0 .Lcf_skip_6_18
	s_add_u32 s100, s68, 0x1631dc40
	s_addc_u32 s101, s69, 0
	global_store_dword v21, v26, s[100:101]
.Lcf_skip_6_18:
	v_fma_f32 v26, v90, v26, v91
	s_cmp_eq_u32 s99, 14
	s_cbranch_scc0 .Lcf_skip_6_19
	s_add_u32 s100, s68, 0x1631cc40
	s_addc_u32 s101, s69, 0
	global_store_dword v21, v26, s[100:101]
.Lcf_skip_6_19:
	v_fma_f32 v26, v92, v26, v93
	s_cmp_eq_u32 s99, 13
	s_cbranch_scc0 .Lcf_skip_6_20
	s_add_u32 s100, s68, 0x1631bc40
	s_addc_u32 s101, s69, 0
	global_store_dword v21, v26, s[100:101]
.Lcf_skip_6_20:
	v_fma_f32 v26, v94, v26, v95
	s_cmp_eq_u32 s99, 12
	s_cbranch_scc0 .Lcf_skip_6_21
	s_add_u32 s100, s68, 0x1631ac40
	s_addc_u32 s101, s69, 0
	global_store_dword v21, v26, s[100:101]
.Lcf_skip_6_21:
	v_fma_f32 v26, v96, v26, v97
	s_cmp_eq_u32 s99, 11
	s_cbranch_scc0 .Lcf_skip_6_22
	s_add_u32 s100, s68, 0x16319c40
	s_addc_u32 s101, s69, 0
	global_store_dword v21, v26, s[100:101]
.Lcf_skip_6_22:
	v_fma_f32 v26, v98, v26, v99
	s_cmp_eq_u32 s99, 10
	s_cbranch_scc0 .Lcf_skip_6_23
	s_add_u32 s100, s68, 0x16318c40
	s_addc_u32 s101, s69, 0
	global_store_dword v21, v26, s[100:101]
.Lcf_skip_6_23:
	v_fma_f32 v26, v100, v26, v101
	s_cmp_eq_u32 s99, 9
	s_cbranch_scc0 .Lcf_skip_6_24
	s_add_u32 s100, s68, 0x16317c40
	s_addc_u32 s101, s69, 0
	global_store_dword v21, v26, s[100:101]
.Lcf_skip_6_24:
	v_fma_f32 v26, v102, v26, v103
	s_cmp_eq_u32 s99, 8
	s_cbranch_scc0 .Lcf_skip_6_25
	s_add_u32 s100, s68, 0x16316c40
	s_addc_u32 s101, s69, 0
	global_store_dword v21, v26, s[100:101]
.Lcf_skip_6_25:
	v_fma_f32 v26, v104, v26, v105
	s_cmp_eq_u32 s99, 7
	s_cbranch_scc0 .Lcf_skip_6_26
	s_add_u32 s100, s68, 0x16315c40
	s_addc_u32 s101, s69, 0
	global_store_dword v21, v26, s[100:101]
.Lcf_skip_6_26:
	v_fma_f32 v26, v106, v26, v107
	s_cmp_eq_u32 s99, 6
	s_cbranch_scc0 .Lcf_skip_6_27
	s_add_u32 s100, s68, 0x16314c40
	s_addc_u32 s101, s69, 0
	global_store_dword v21, v26, s[100:101]
.Lcf_skip_6_27:
	v_fma_f32 v26, v108, v26, v109
	s_cmp_eq_u32 s99, 5
	s_cbranch_scc0 .Lcf_skip_6_28
	s_add_u32 s100, s68, 0x16313c40
	s_addc_u32 s101, s69, 0
	global_store_dword v21, v26, s[100:101]
.Lcf_skip_6_28:
	v_fma_f32 v26, v110, v26, v111
	s_cmp_eq_u32 s99, 4
	s_cbranch_scc0 .Lcf_skip_6_29
	s_add_u32 s100, s68, 0x16312c40
	s_addc_u32 s101, s69, 0
	global_store_dword v21, v26, s[100:101]
.Lcf_skip_6_29:
	v_fma_f32 v26, v112, v26, v113
	s_cmp_eq_u32 s99, 3
	s_cbranch_scc0 .Lcf_skip_6_30
	s_add_u32 s100, s68, 0x16311c40
	s_addc_u32 s101, s69, 0
	global_store_dword v21, v26, s[100:101]
.Lcf_skip_6_30:
	v_fma_f32 v26, v114, v26, v115
	s_cmp_eq_u32 s99, 2
	s_cbranch_scc0 .Lcf_skip_6_31
	s_add_u32 s100, s68, 0x16310c40
	s_addc_u32 s101, s69, 0
	global_store_dword v21, v26, s[100:101]
.Lcf_skip_6_31:
	v_fma_f32 v26, v116, v26, v117
	s_cmp_eq_u32 s99, 1
	s_cbranch_scc0 .Lcf_skip_6_32
	s_add_u32 s100, s68, 0x1630fc40
	s_addc_u32 s101, s69, 0
	global_store_dword v21, v26, s[100:101]

.Lcf_var_7:
	s_add_u32 s100, s68, 0x161a8c40
	s_addc_u32 s101, s69, 0
	global_load_dwordx2 v[48:49], v20, s[100:101]
	s_add_u32 s100, s68, 0x161a6c40
	s_addc_u32 s101, s69, 0
	global_load_dwordx2 v[50:51], v20, s[100:101]
	s_add_u32 s100, s68, 0x161a4c40
	s_addc_u32 s101, s69, 0
	global_load_dwordx2 v[52:53], v20, s[100:101]
	s_add_u32 s100, s68, 0x161a2c40
	s_addc_u32 s101, s69, 0
	global_load_dwordx2 v[54:55], v20, s[100:101]
	s_add_u32 s100, s68, 0x161a0c40
	s_addc_u32 s101, s69, 0
	global_load_dwordx2 v[56:57], v20, s[100:101]
	s_add_u32 s100, s68, 0x1619ec40
	s_addc_u32 s101, s69, 0
	global_load_dwordx2 v[58:59], v20, s[100:101]
	s_add_u32 s100, s68, 0x1619cc40
	s_addc_u32 s101, s69, 0
	global_load_dwordx2 v[60:61], v20, s[100:101]
	s_add_u32 s100, s68, 0x1619ac40
	s_addc_u32 s101, s69, 0
	global_load_dwordx2 v[62:63], v20, s[100:101]
	s_add_u32 s100, s68, 0x16198c40
	s_addc_u32 s101, s69, 0
	global_load_dwordx2 v[64:65], v20, s[100:101]
	s_add_u32 s100, s68, 0x16196c40
	s_addc_u32 s101, s69, 0
	global_load_dwordx2 v[66:67], v20, s[100:101]
	s_add_u32 s100, s68, 0x16194c40
	s_addc_u32 s101, s69, 0
	global_load_dwordx2 v[68:69], v20, s[100:101]
	s_add_u32 s100, s68, 0x16192c40
	s_addc_u32 s101, s69, 0
	global_load_dwordx2 v[70:71], v20, s[100:101]
	s_add_u32 s100, s68, 0x16190c40
	s_addc_u32 s101, s69, 0
	global_load_dwordx2 v[78:79], v20, s[100:101]
	s_add_u32 s100, s68, 0x1618ec40
	s_addc_u32 s101, s69, 0
	global_load_dwordx2 v[80:81], v20, s[100:101]
	s_add_u32 s100, s68, 0x1618cc40
	s_addc_u32 s101, s69, 0
	global_load_dwordx2 v[82:83], v20, s[100:101]
	s_add_u32 s100, s68, 0x1618ac40
	s_addc_u32 s101, s69, 0
	global_load_dwordx2 v[84:85], v20, s[100:101]
	s_add_u32 s100, s68, 0x16188c40
	s_addc_u32 s101, s69, 0
	global_load_dwordx2 v[86:87], v20, s[100:101]
	s_add_u32 s100, s68, 0x16186c40
	s_addc_u32 s101, s69, 0
	global_load_dwordx2 v[88:89], v20, s[100:101]
	s_add_u32 s100, s68, 0x16184c40
	s_addc_u32 s101, s69, 0
	global_load_dwordx2 v[90:91], v20, s[100:101]
	s_add_u32 s100, s68, 0x16182c40
	s_addc_u32 s101, s69, 0
	global_load_dwordx2 v[92:93], v20, s[100:101]
	s_add_u32 s100, s68, 0x16180c40
	s_addc_u32 s101, s69, 0
	global_load_dwordx2 v[94:95], v20, s[100:101]
	s_add_u32 s100, s68, 0x1617ec40
	s_addc_u32 s101, s69, 0
	global_load_dwordx2 v[96:97], v20, s[100:101]
	s_add_u32 s100, s68, 0x1617cc40
	s_addc_u32 s101, s69, 0
	global_load_dwordx2 v[98:99], v20, s[100:101]
	s_add_u32 s100, s68, 0x1617ac40
	s_addc_u32 s101, s69, 0
	global_load_dwordx2 v[100:101], v20, s[100:101]
	s_add_u32 s100, s68, 0x16178c40
	s_addc_u32 s101, s69, 0
	global_load_dwordx2 v[102:103], v20, s[100:101]
	s_add_u32 s100, s68, 0x16176c40
	s_addc_u32 s101, s69, 0
	global_load_dwordx2 v[104:105], v20, s[100:101]
	s_add_u32 s100, s68, 0x16174c40
	s_addc_u32 s101, s69, 0
	global_load_dwordx2 v[106:107], v20, s[100:101]
	s_add_u32 s100, s68, 0x16172c40
	s_addc_u32 s101, s69, 0
	global_load_dwordx2 v[108:109], v20, s[100:101]
	s_add_u32 s100, s68, 0x16170c40
	s_addc_u32 s101, s69, 0
	global_load_dwordx2 v[110:111], v20, s[100:101]
	s_add_u32 s100, s68, 0x1616ec40
	s_addc_u32 s101, s69, 0
	global_load_dwordx2 v[112:113], v20, s[100:101]
	s_add_u32 s100, s68, 0x1616cc40
	s_addc_u32 s101, s69, 0
	global_load_dwordx2 v[114:115], v20, s[100:101]
	v_mov_b32_e32 v24, 1.0
	v_mov_b32_e32 v25, 0
	s_waitcnt vmcnt(30)
	v_fma_f32 v25, v48, v25, v49
	v_mul_f32_e32 v24, v24, v48
	s_waitcnt vmcnt(29)
	v_fma_f32 v25, v50, v25, v51
	v_mul_f32_e32 v24, v24, v50
	s_waitcnt vmcnt(28)
	v_fma_f32 v25, v52, v25, v53
	v_mul_f32_e32 v24, v24, v52
	s_waitcnt vmcnt(27)
	v_fma_f32 v25, v54, v25, v55
	v_mul_f32_e32 v24, v24, v54
	s_waitcnt vmcnt(26)
	v_fma_f32 v25, v56, v25, v57
	v_mul_f32_e32 v24, v24, v56
	s_waitcnt vmcnt(25)
	v_fma_f32 v25, v58, v25, v59
	v_mul_f32_e32 v24, v24, v58
	s_waitcnt vmcnt(24)
	v_fma_f32 v25, v60, v25, v61
	v_mul_f32_e32 v24, v24, v60
	s_waitcnt vmcnt(23)
	v_fma_f32 v25, v62, v25, v63
	v_mul_f32_e32 v24, v24, v62
	s_waitcnt vmcnt(22)
	v_fma_f32 v25, v64, v25, v65
	v_mul_f32_e32 v24, v24, v64
	s_waitcnt vmcnt(21)
	v_fma_f32 v25, v66, v25, v67
	v_mul_f32_e32 v24, v24, v66
	s_waitcnt vmcnt(20)
	v_fma_f32 v25, v68, v25, v69
	v_mul_f32_e32 v24, v24, v68
	s_waitcnt vmcnt(19)
	v_fma_f32 v25, v70, v25, v71
	v_mul_f32_e32 v24, v24, v70
	s_waitcnt vmcnt(18)
	v_fma_f32 v25, v78, v25, v79
	v_mul_f32_e32 v24, v24, v78
	s_waitcnt vmcnt(17)
	v_fma_f32 v25, v80, v25, v81
	v_mul_f32_e32 v24, v24, v80
	s_waitcnt vmcnt(16)
	v_fma_f32 v25, v82, v25, v83
	v_mul_f32_e32 v24, v24, v82
	s_waitcnt vmcnt(15)
	v_fma_f32 v25, v84, v25, v85
	v_mul_f32_e32 v24, v24, v84
	s_waitcnt vmcnt(14)
	v_fma_f32 v25, v86, v25, v87
	v_mul_f32_e32 v24, v24, v86
	s_waitcnt vmcnt(13)
	v_fma_f32 v25, v88, v25, v89
	v_mul_f32_e32 v24, v24, v88
	s_waitcnt vmcnt(12)
	v_fma_f32 v25, v90, v25, v91
	v_mul_f32_e32 v24, v24, v90
	s_waitcnt vmcnt(11)
	v_fma_f32 v25, v92, v25, v93
	v_mul_f32_e32 v24, v24, v92
	s_waitcnt vmcnt(10)
	v_fma_f32 v25, v94, v25, v95
	v_mul_f32_e32 v24, v24, v94
	s_waitcnt vmcnt(9)
	v_fma_f32 v25, v96, v25, v97
	v_mul_f32_e32 v24, v24, v96
	s_waitcnt vmcnt(8)
	v_fma_f32 v25, v98, v25, v99
	v_mul_f32_e32 v24, v24, v98
	s_waitcnt vmcnt(7)
	v_fma_f32 v25, v100, v25, v101
	v_mul_f32_e32 v24, v24, v100
	s_waitcnt vmcnt(6)
	v_fma_f32 v25, v102, v25, v103
	v_mul_f32_e32 v24, v24, v102
	s_waitcnt vmcnt(5)
	v_fma_f32 v25, v104, v25, v105
	v_mul_f32_e32 v24, v24, v104
	s_waitcnt vmcnt(4)
	v_fma_f32 v25, v106, v25, v107
	v_mul_f32_e32 v24, v24, v106
	s_waitcnt vmcnt(3)
	v_fma_f32 v25, v108, v25, v109
	v_mul_f32_e32 v24, v24, v108
	s_waitcnt vmcnt(2)
	v_fma_f32 v25, v110, v25, v111
	v_mul_f32_e32 v24, v24, v110
	s_waitcnt vmcnt(1)
	v_fma_f32 v25, v112, v25, v113
	v_mul_f32_e32 v24, v24, v112
	s_waitcnt vmcnt(0)
	v_fma_f32 v25, v114, v25, v115
	v_mul_f32_e32 v24, v24, v114
	ds_write_b64 v22, v[24:25] offset:3584
	s_waitcnt lgkmcnt(0)
	s_barrier
	v_mov_b32_e32 v26, 0
	ds_read_b64 v[28:29], v22 offset:2048
	s_waitcnt lgkmcnt(0)
	v_fma_f32 v26, v28, v26, v29
	ds_read_b64 v[28:29], v22 offset:2560
	s_waitcnt lgkmcnt(0)
	v_fma_f32 v26, v28, v26, v29
	ds_read_b64 v[28:29], v22 offset:3072
	s_waitcnt lgkmcnt(0)
	v_fma_f32 v26, v28, v26, v29
	s_cmp_eq_u32 s99, 0
	s_cbranch_scc0 .Lcf_skip_7_0
	s_add_u32 s100, s68, 0x1630ec40
	s_addc_u32 s101, s69, 0
	global_store_dword v21, v26, s[100:101]
.Lcf_skip_7_0:
	v_fma_f32 v26, v48, v26, v49
	s_cmp_eq_u32 s99, 15
	s_cbranch_scc0 .Lcf_skip_7_1
	s_add_u32 s100, s68, 0x1630dc40
	s_addc_u32 s101, s69, 0
	global_store_dword v21, v26, s[100:101]
.Lcf_skip_7_1:
	v_fma_f32 v26, v50, v26, v51
	s_cmp_eq_u32 s99, 14
	s_cbranch_scc0 .Lcf_skip_7_2
	s_add_u32 s100, s68, 0x1630cc40
	s_addc_u32 s101, s69, 0
	global_store_dword v21, v26, s[100:101]
.Lcf_skip_7_2:
	v_fma_f32 v26, v52, v26, v53
	s_cmp_eq_u32 s99, 13
	s_cbranch_scc0 .Lcf_skip_7_3
	s_add_u32 s100, s68, 0x1630bc40
	s_addc_u32 s101, s69, 0
	global_store_dword v21, v26, s[100:101]
.Lcf_skip_7_3:
	v_fma_f32 v26, v54, v26, v55
	s_cmp_eq_u32 s99, 12
	s_cbranch_scc0 .Lcf_skip_7_4
	s_add_u32 s100, s68, 0x1630ac40
	s_addc_u32 s101, s69, 0
	global_store_dword v21, v26, s[100:101]
.Lcf_skip_7_4:
	v_fma_f32 v26, v56, v26, v57
	s_cmp_eq_u32 s99, 11
	s_cbranch_scc0 .Lcf_skip_7_5
	s_add_u32 s100, s68, 0x16309c40
	s_addc_u32 s101, s69, 0
	global_store_dword v21, v26, s[100:101]
.Lcf_skip_7_5:
	v_fma_f32 v26, v58, v26, v59
	s_cmp_eq_u32 s99, 10
	s_cbranch_scc0 .Lcf_skip_7_6
	s_add_u32 s100, s68, 0x16308c40
	s_addc_u32 s101, s69, 0
	global_store_dword v21, v26, s[100:101]
.Lcf_skip_7_6:
	v_fma_f32 v26, v60, v26, v61
	s_cmp_eq_u32 s99, 9
	s_cbranch_scc0 .Lcf_skip_7_7
	s_add_u32 s100, s68, 0x16307c40
	s_addc_u32 s101, s69, 0
	global_store_dword v21, v26, s[100:101]
.Lcf_skip_7_7:
	v_fma_f32 v26, v62, v26, v63
	s_cmp_eq_u32 s99, 8
	s_cbranch_scc0 .Lcf_skip_7_8
	s_add_u32 s100, s68, 0x16306c40
	s_addc_u32 s101, s69, 0
	global_store_dword v21, v26, s[100:101]
.Lcf_skip_7_8:
	v_fma_f32 v26, v64, v26, v65
	s_cmp_eq_u32 s99, 7
	s_cbranch_scc0 .Lcf_skip_7_9
	s_add_u32 s100, s68, 0x16305c40
	s_addc_u32 s101, s69, 0
	global_store_dword v21, v26, s[100:101]
.Lcf_skip_7_9:
	v_fma_f32 v26, v66, v26, v67
	s_cmp_eq_u32 s99, 6
	s_cbranch_scc0 .Lcf_skip_7_10
	s_add_u32 s100, s68, 0x16304c40
	s_addc_u32 s101, s69, 0
	global_store_dword v21, v26, s[100:101]
.Lcf_skip_7_10:
	v_fma_f32 v26, v68, v26, v69
	s_cmp_eq_u32 s99, 5
	s_cbranch_scc0 .Lcf_skip_7_11
	s_add_u32 s100, s68, 0x16303c40
	s_addc_u32 s101, s69, 0
	global_store_dword v21, v26, s[100:101]
.Lcf_skip_7_11:
	v_fma_f32 v26, v70, v26, v71
	s_cmp_eq_u32 s99, 4
	s_cbranch_scc0 .Lcf_skip_7_12
	s_add_u32 s100, s68, 0x16302c40
	s_addc_u32 s101, s69, 0
	global_store_dword v21, v26, s[100:101]
.Lcf_skip_7_12:
	v_fma_f32 v26, v78, v26, v79
	s_cmp_eq_u32 s99, 3
	s_cbranch_scc0 .Lcf_skip_7_13
	s_add_u32 s100, s68, 0x16301c40
	s_addc_u32 s101, s69, 0
	global_store_dword v21, v26, s[100:101]
.Lcf_skip_7_13:
	v_fma_f32 v26, v80, v26, v81
	s_cmp_eq_u32 s99, 2
	s_cbranch_scc0 .Lcf_skip_7_14
	s_add_u32 s100, s68, 0x16300c40
	s_addc_u32 s101, s69, 0
	global_store_dword v21, v26, s[100:101]
.Lcf_skip_7_14:
	v_fma_f32 v26, v82, v26, v83
	s_cmp_eq_u32 s99, 1
	s_cbranch_scc0 .Lcf_skip_7_15
	s_add_u32 s100, s68, 0x162ffc40
	s_addc_u32 s101, s69, 0
	global_store_dword v21, v26, s[100:101]
.Lcf_skip_7_15:
	v_fma_f32 v26, v84, v26, v85
	s_cmp_eq_u32 s99, 0
	s_cbranch_scc0 .Lcf_skip_7_16
	s_add_u32 s100, s68, 0x162fec40
	s_addc_u32 s101, s69, 0
	global_store_dword v21, v26, s[100:101]
.Lcf_skip_7_16:
	v_fma_f32 v26, v86, v26, v87
	s_cmp_eq_u32 s99, 15
	s_cbranch_scc0 .Lcf_skip_7_17
	s_add_u32 s100, s68, 0x162fdc40
	s_addc_u32 s101, s69, 0
	global_store_dword v21, v26, s[100:101]
.Lcf_skip_7_17:
	v_fma_f32 v26, v88, v26, v89
	s_cmp_eq_u32 s99, 14
	s_cbranch_scc0 .Lcf_skip_7_18
	s_add_u32 s100, s68, 0x162fcc40
	s_addc_u32 s101, s69, 0
	global_store_dword v21, v26, s[100:101]
.Lcf_skip_7_18:
	v_fma_f32 v26, v90, v26, v91
	s_cmp_eq_u32 s99, 13
	s_cbranch_scc0 .Lcf_skip_7_19
	s_add_u32 s100, s68, 0x162fbc40
	s_addc_u32 s101, s69, 0
	global_store_dword v21, v26, s[100:101]
.Lcf_skip_7_19:
	v_fma_f32 v26, v92, v26, v93
	s_cmp_eq_u32 s99, 12
	s_cbranch_scc0 .Lcf_skip_7_20
	s_add_u32 s100, s68, 0x162fac40
	s_addc_u32 s101, s69, 0
	global_store_dword v21, v26, s[100:101]
.Lcf_skip_7_20:
	v_fma_f32 v26, v94, v26, v95
	s_cmp_eq_u32 s99, 11
	s_cbranch_scc0 .Lcf_skip_7_21
	s_add_u32 s100, s68, 0x162f9c40
	s_addc_u32 s101, s69, 0
	global_store_dword v21, v26, s[100:101]
.Lcf_skip_7_21:
	v_fma_f32 v26, v96, v26, v97
	s_cmp_eq_u32 s99, 10
	s_cbranch_scc0 .Lcf_skip_7_22
	s_add_u32 s100, s68, 0x162f8c40
	s_addc_u32 s101, s69, 0
	global_store_dword v21, v26, s[100:101]
.Lcf_skip_7_22:
	v_fma_f32 v26, v98, v26, v99
	s_cmp_eq_u32 s99, 9
	s_cbranch_scc0 .Lcf_skip_7_23
	s_add_u32 s100, s68, 0x162f7c40
	s_addc_u32 s101, s69, 0
	global_store_dword v21, v26, s[100:101]
.Lcf_skip_7_23:
	v_fma_f32 v26, v100, v26, v101
	s_cmp_eq_u32 s99, 8
	s_cbranch_scc0 .Lcf_skip_7_24
	s_add_u32 s100, s68, 0x162f6c40
	s_addc_u32 s101, s69, 0
	global_store_dword v21, v26, s[100:101]
.Lcf_skip_7_24:
	v_fma_f32 v26, v102, v26, v103
	s_cmp_eq_u32 s99, 7
	s_cbranch_scc0 .Lcf_skip_7_25
	s_add_u32 s100, s68, 0x162f5c40
	s_addc_u32 s101, s69, 0
	global_store_dword v21, v26, s[100:101]
.Lcf_skip_7_25:
	v_fma_f32 v26, v104, v26, v105
	s_cmp_eq_u32 s99, 6
	s_cbranch_scc0 .Lcf_skip_7_26
	s_add_u32 s100, s68, 0x162f4c40
	s_addc_u32 s101, s69, 0
	global_store_dword v21, v26, s[100:101]
.Lcf_skip_7_26:
	v_fma_f32 v26, v106, v26, v107
	s_cmp_eq_u32 s99, 5
	s_cbranch_scc0 .Lcf_skip_7_27
	s_add_u32 s100, s68, 0x162f3c40
	s_addc_u32 s101, s69, 0
	global_store_dword v21, v26, s[100:101]
.Lcf_skip_7_27:
	v_fma_f32 v26, v108, v26, v109
	s_cmp_eq_u32 s99, 4
	s_cbranch_scc0 .Lcf_skip_7_28
	s_add_u32 s100, s68, 0x162f2c40
	s_addc_u32 s101, s69, 0
	global_store_dword v21, v26, s[100:101]
.Lcf_skip_7_28:
	v_fma_f32 v26, v110, v26, v111
	s_cmp_eq_u32 s99, 3
	s_cbranch_scc0 .Lcf_skip_7_29
	s_add_u32 s100, s68, 0x162f1c40
	s_addc_u32 s101, s69, 0
	global_store_dword v21, v26, s[100:101]
.Lcf_skip_7_29:
	v_fma_f32 v26, v112, v26, v113
	s_cmp_eq_u32 s99, 2
	s_cbranch_scc0 .Lcf_skip_7_30
	s_add_u32 s100, s68, 0x162f0c40
	s_addc_u32 s101, s69, 0
	global_store_dword v21, v26, s[100:101]

.Lcf_join:
	s_waitcnt vmcnt(0)
	s_barrier
	s_branch .LBB0_595

	.amdhsa_kernel _Z8mega_fwd4Args
		.amdhsa_group_segment_fixed_size 0
		.amdhsa_private_segment_fixed_size 0
		.amdhsa_kernarg_size 480
		.amdhsa_user_sgpr_count 2
		.amdhsa_user_sgpr_dispatch_ptr 0
		.amdhsa_user_sgpr_queue_ptr 0
		.amdhsa_user_sgpr_kernarg_segment_ptr 1
		.amdhsa_user_sgpr_dispatch_id 0
		.amdhsa_user_sgpr_kernarg_preload_length 0
		.amdhsa_user_sgpr_kernarg_preload_offset 0
		.amdhsa_user_sgpr_private_segment_size 0
		.amdhsa_uses_dynamic_stack 0
		.amdhsa_enable_private_segment 0
		.amdhsa_system_sgpr_workgroup_id_x 1
		.amdhsa_system_sgpr_workgroup_id_y 0
		.amdhsa_system_sgpr_workgroup_id_z 0
		.amdhsa_system_sgpr_workgroup_info 0
		.amdhsa_system_vgpr_workitem_id 2
		.amdhsa_next_free_vgpr 246
		.amdhsa_next_free_sgpr 102
		.amdhsa_accum_offset 248
		.amdhsa_reserve_vcc 1
		.amdhsa_float_round_mode_32 0
		.amdhsa_float_round_mode_16_64 0
		.amdhsa_float_denorm_mode_32 3
		.amdhsa_float_denorm_mode_16_64 3
		.amdhsa_dx10_clamp 1
		.amdhsa_ieee_mode 1
		.amdhsa_fp16_overflow 0
		.amdhsa_tg_split 0
		.amdhsa_exception_fp_ieee_invalid_op 0
		.amdhsa_exception_fp_denorm_src 0
		.amdhsa_exception_fp_ieee_div_zero 0
		.amdhsa_exception_fp_ieee_overflow 0
		.amdhsa_exception_fp_ieee_underflow 0
		.amdhsa_exception_fp_ieee_inexact 0
		.amdhsa_exception_int_div_zero 0
	.end_amdhsa_kernel

amdhsa.kernels:
  - .agpr_count:     0
    .args:
      - .offset:         0
        .size:           224
        .value_kind:     by_value
      - .offset:         224
        .size:           4
        .value_kind:     hidden_block_count_x
      - .offset:         228
        .size:           4
        .value_kind:     hidden_block_count_y
      - .offset:         232
        .size:           4
        .value_kind:     hidden_block_count_z
      - .offset:         236
        .size:           2
        .value_kind:     hidden_group_size_x
      - .offset:         238
        .size:           2
        .value_kind:     hidden_group_size_y
      - .offset:         240
        .size:           2
        .value_kind:     hidden_group_size_z
      - .offset:         242
        .size:           2
        .value_kind:     hidden_remainder_x
      - .offset:         244
        .size:           2
        .value_kind:     hidden_remainder_y
      - .offset:         246
        .size:           2
        .value_kind:     hidden_remainder_z
      - .offset:         264
        .size:           8
        .value_kind:     hidden_global_offset_x
      - .offset:         272
        .size:           8
        .value_kind:     hidden_global_offset_y
      - .offset:         280
        .size:           8
        .value_kind:     hidden_global_offset_z
      - .offset:         288
        .size:           2
        .value_kind:     hidden_grid_dims
      - .offset:         312
        .size:           8
        .value_kind:     hidden_multigrid_sync_arg
      - .offset:         344
        .size:           4
        .value_kind:     hidden_dynamic_lds_size
    .group_segment_fixed_size: 0
    .kernarg_segment_align: 8
    .kernarg_segment_size: 480
    .language:       OpenCL C
    .language_version:
      - 2
      - 0
    .max_flat_workgroup_size: 512
    .name:           _Z8mega_fwd4Args
    .private_segment_fixed_size: 0
    .sgpr_count:     108
    .sgpr_spill_count: 182
    .symbol:         _Z8mega_fwd4Args.kd
    .uniform_work_group_size: 1
    .uses_dynamic_stack: false
    .vgpr_count:     246
    .vgpr_spill_count: 0
    .wavefront_size: 64
